# cache policy: nt on the once-read f32 weight loads of the in-kernel weight conversion loops (each element is read by exactly one wave once), on top of v18
# speedup vs baseline: 1.0264x; 1.0264x over previous
.LBB0_10:
	s_mul_hi_i32 s12, s18, 0x2aaaaaab
	s_lshr_b32 s13, s12, 31
	s_ashr_i32 s12, s12, 3
	s_add_i32 s13, s12, s13
	s_lshl_b32 s12, s13, 5
	s_mulk_i32 s13, 0xf400
	s_add_i32 s19, s16, s13
	s_and_b32 s13, s19, 0xffffff00
	s_lshr_b32 s20, s19, 2
	v_and_b32_e32 v6, 0xc0, v41
	s_and_b32 s20, s20, 32
	v_or_b32_e32 v7, s13, v38
	v_or3_b32 v6, v7, s20, v6
	v_ashrrev_i32_e32 v7, 31, v6
	v_lshl_add_u64 v[30:31], v[6:7], 2, s[10:11]
	s_or_b32 s13, s12, 1
	v_mad_i64_i32 v[16:17], s[20:21], s13, v42, v[30:31]
	s_or_b32 s13, s12, 2
	v_mad_i64_i32 v[18:19], s[20:21], s13, v42, v[30:31]
	s_or_b32 s13, s12, 3
	v_mad_i64_i32 v[20:21], s[20:21], s13, v42, v[30:31]
	s_or_b32 s13, s12, 4
	v_mad_i64_i32 v[22:23], s[20:21], s13, v42, v[30:31]
	s_or_b32 s13, s12, 5
	v_mad_i64_i32 v[24:25], s[20:21], s13, v42, v[30:31]
	s_or_b32 s13, s12, 6
	v_mad_i64_i32 v[26:27], s[20:21], s13, v42, v[30:31]
	s_or_b32 s13, s12, 7
	v_mad_i64_i32 v[14:15], s[20:21], s12, v42, v[30:31]
	v_mad_i64_i32 v[28:29], s[20:21], s13, v42, v[30:31]
	s_or_b32 s13, s12, 8
	global_load_dword v6, v[14:15], off nt
	global_load_dword v7, v[16:17], off nt
	global_load_dword v10, v[18:19], off nt
	global_load_dword v11, v[20:21], off nt
	global_load_dword v8, v[22:23], off nt
	global_load_dword v9, v[24:25], off nt
	global_load_dword v12, v[26:27], off nt
	global_load_dword v13, v[28:29], off nt
	v_mad_i64_i32 v[22:23], s[20:21], s13, v42, v[30:31]
	s_or_b32 s13, s12, 9
	v_mad_i64_i32 v[24:25], s[20:21], s13, v42, v[30:31]
	s_or_b32 s13, s12, 10
	v_mad_i64_i32 v[26:27], s[20:21], s13, v42, v[30:31]
	s_or_b32 s13, s12, 11
	v_mad_i64_i32 v[28:29], s[20:21], s13, v42, v[30:31]
	s_or_b32 s13, s12, 12
	v_mad_i64_i32 v[32:33], s[20:21], s13, v42, v[30:31]
	s_or_b32 s13, s12, 13
	v_mad_i64_i32 v[34:35], s[20:21], s13, v42, v[30:31]
	s_or_b32 s13, s12, 14
	v_mad_i64_i32 v[36:37], s[20:21], s13, v42, v[30:31]
	s_or_b32 s13, s12, 15
	v_mad_i64_i32 v[44:45], s[20:21], s13, v42, v[30:31]
	s_or_b32 s13, s12, 16
	global_load_dword v14, v[22:23], off nt
	global_load_dword v15, v[24:25], off nt
	global_load_dword v18, v[26:27], off nt
	global_load_dword v19, v[28:29], off nt
	global_load_dword v16, v[32:33], off nt
	global_load_dword v17, v[34:35], off nt
	global_load_dword v20, v[36:37], off nt
	global_load_dword v21, v[44:45], off nt
	v_mad_i64_i32 v[32:33], s[20:21], s13, v42, v[30:31]
	s_or_b32 s13, s12, 17
	v_mad_i64_i32 v[34:35], s[20:21], s13, v42, v[30:31]
	s_or_b32 s13, s12, 18
	v_mad_i64_i32 v[36:37], s[20:21], s13, v42, v[30:31]
	s_or_b32 s13, s12, 19
	v_mad_i64_i32 v[44:45], s[20:21], s13, v42, v[30:31]
	s_or_b32 s13, s12, 20
	v_mad_i64_i32 v[46:47], s[20:21], s13, v42, v[30:31]
	s_or_b32 s13, s12, 21
	v_mad_i64_i32 v[48:49], s[20:21], s13, v42, v[30:31]
	s_or_b32 s13, s12, 22
	v_mad_i64_i32 v[50:51], s[20:21], s13, v42, v[30:31]
	s_or_b32 s13, s12, 23
	v_mad_i64_i32 v[52:53], s[20:21], s13, v42, v[30:31]
	s_or_b32 s13, s12, 24
	global_load_dword v22, v[32:33], off nt
	global_load_dword v23, v[34:35], off nt
	global_load_dword v26, v[36:37], off nt
	global_load_dword v27, v[44:45], off nt
	global_load_dword v24, v[46:47], off nt
	global_load_dword v25, v[48:49], off nt
	global_load_dword v28, v[50:51], off nt
	global_load_dword v29, v[52:53], off nt
	v_mad_i64_i32 v[44:45], s[20:21], s13, v42, v[30:31]
	s_or_b32 s13, s12, 25
	v_mad_i64_i32 v[46:47], s[20:21], s13, v42, v[30:31]
	s_or_b32 s13, s12, 26
	v_mad_i64_i32 v[48:49], s[20:21], s13, v42, v[30:31]
	s_or_b32 s13, s12, 27
	v_mad_i64_i32 v[50:51], s[20:21], s13, v42, v[30:31]
	s_or_b32 s13, s12, 28
	v_mad_i64_i32 v[52:53], s[20:21], s13, v42, v[30:31]
	s_or_b32 s13, s12, 29
	v_mad_i64_i32 v[54:55], s[20:21], s13, v42, v[30:31]
	s_or_b32 s13, s12, 30
	v_mad_i64_i32 v[56:57], s[20:21], s13, v42, v[30:31]
	s_or_b32 s13, s12, 31
	v_mad_i64_i32 v[58:59], s[20:21], s13, v42, v[30:31]
	global_load_dword v30, v[44:45], off nt
	global_load_dword v31, v[46:47], off nt
	global_load_dword v36, v[48:49], off nt
	global_load_dword v37, v[50:51], off nt
	global_load_dword v34, v[52:53], off nt
	global_load_dword v35, v[54:55], off nt
	global_load_dword v32, v[56:57], off nt
	global_load_dword v33, v[58:59], off nt
	s_and_b64 vcc, exec, s[6:7]
	s_ashr_i32 s13, s12, 31
	s_cbranch_vccnz .LBB0_9
	s_lshl_b64 s[20:21], s[12:13], 2
	s_add_u32 s20, s8, s20
	s_addc_u32 s21, s9, s21
	global_load_dwordx4 v[44:47], v3, s[20:21]
	global_load_dwordx4 v[48:51], v3, s[20:21] offset:16
	global_load_dwordx4 v[52:55], v3, s[20:21] offset:32
	global_load_dwordx4 v[56:59], v3, s[20:21] offset:48
	global_load_dwordx4 v[60:63], v3, s[20:21] offset:64
	global_load_dwordx4 v[64:67], v3, s[20:21] offset:80
	global_load_dwordx4 v[68:71], v3, s[20:21] offset:96
	global_load_dwordx4 v[72:75], v3, s[20:21] offset:112
	s_waitcnt vmcnt(7)
	v_pk_mul_f32 v[6:7], v[6:7], v[44:45]
	v_pk_mul_f32 v[10:11], v[10:11], v[46:47]
	s_waitcnt vmcnt(6)
	v_pk_mul_f32 v[8:9], v[8:9], v[48:49]
	v_pk_mul_f32 v[12:13], v[12:13], v[50:51]
	s_waitcnt vmcnt(5)
	v_pk_mul_f32 v[14:15], v[14:15], v[52:53]
	v_pk_mul_f32 v[18:19], v[18:19], v[54:55]
	s_waitcnt vmcnt(4)
	v_pk_mul_f32 v[16:17], v[16:17], v[56:57]
	v_pk_mul_f32 v[20:21], v[20:21], v[58:59]
	s_waitcnt vmcnt(3)
	v_pk_mul_f32 v[22:23], v[22:23], v[60:61]
	v_pk_mul_f32 v[26:27], v[26:27], v[62:63]
	s_waitcnt vmcnt(2)
	v_pk_mul_f32 v[24:25], v[24:25], v[64:65]
	v_pk_mul_f32 v[28:29], v[28:29], v[66:67]
	s_waitcnt vmcnt(1)
	v_pk_mul_f32 v[30:31], v[30:31], v[68:69]
	v_pk_mul_f32 v[36:37], v[36:37], v[70:71]
	s_waitcnt vmcnt(0)
	v_pk_mul_f32 v[34:35], v[34:35], v[72:73]
	v_pk_mul_f32 v[32:33], v[32:33], v[74:75]
	s_branch .LBB0_9

.LBB0_14:
	s_ashr_i32 s8, s65, 31
	s_lshr_b32 s8, s8, 28
	s_add_i32 s8, s65, s8
	s_ashr_i32 s9, s8, 4
	s_lshl_b32 s8, s9, 5
	s_lshl_b32 s9, s9, 10
	s_sub_i32 s66, s63, s9
	s_or_b32 s10, s8, 1
	s_or_b32 s12, s8, 2
	s_or_b32 s14, s8, 3
	s_or_b32 s16, s8, 4
	s_or_b32 s18, s8, 5
	s_or_b32 s20, s8, 6
	s_or_b32 s24, s8, 8
	s_or_b32 s28, s8, 10
	s_or_b32 s30, s8, 11
	s_or_b32 s34, s8, 12
	s_or_b32 s36, s8, 13
	s_or_b32 s38, s8, 14
	v_add_u32_e32 v16, s66, v7
	s_ashr_i32 s9, s8, 31
	s_or_b32 s22, s8, 7
	s_or_b32 s26, s8, 9
	s_or_b32 s40, s8, 15
	s_or_b32 s42, s8, 16
	s_or_b32 s44, s8, 17
	s_or_b32 s46, s8, 18
	s_or_b32 s48, s8, 19
	s_or_b32 s50, s8, 20
	s_or_b32 s52, s8, 21
	s_or_b32 s54, s8, 22
	s_or_b32 s56, s8, 23
	s_or_b32 s58, s8, 24
	s_or_b32 s60, s8, 25
	s_or_b32 s68, s8, 26
	s_or_b32 s70, s8, 27
	s_or_b32 s72, s8, 28
	s_or_b32 s74, s8, 29
	s_or_b32 s76, s8, 30
	s_or_b32 s78, s8, 31
	s_ashr_i32 s11, s10, 31
	s_ashr_i32 s13, s12, 31
	s_ashr_i32 s15, s14, 31
	s_ashr_i32 s17, s16, 31
	s_ashr_i32 s19, s18, 31
	s_ashr_i32 s21, s20, 31
	s_ashr_i32 s25, s24, 31
	s_ashr_i32 s29, s28, 31
	s_ashr_i32 s31, s30, 31
	s_ashr_i32 s35, s34, 31
	s_ashr_i32 s37, s36, 31
	s_ashr_i32 s39, s38, 31
	v_ashrrev_i32_e32 v17, 31, v16
	s_lshl_b64 s[80:81], s[8:9], 12
	s_ashr_i32 s23, s22, 31
	s_ashr_i32 s27, s26, 31
	s_ashr_i32 s41, s40, 31
	s_ashr_i32 s43, s42, 31
	s_ashr_i32 s45, s44, 31
	s_ashr_i32 s47, s46, 31
	s_ashr_i32 s49, s48, 31
	s_ashr_i32 s51, s50, 31
	s_ashr_i32 s53, s52, 31
	s_ashr_i32 s55, s54, 31
	s_ashr_i32 s57, s56, 31
	s_ashr_i32 s59, s58, 31
	s_ashr_i32 s61, s60, 31
	s_ashr_i32 s69, s68, 31
	s_ashr_i32 s71, s70, 31
	s_ashr_i32 s73, s72, 31
	s_ashr_i32 s75, s74, 31
	s_ashr_i32 s77, s76, 31
	s_ashr_i32 s79, s78, 31
	s_lshl_b64 s[10:11], s[10:11], 12
	s_lshl_b64 s[12:13], s[12:13], 12
	s_lshl_b64 s[14:15], s[14:15], 12
	s_lshl_b64 s[16:17], s[16:17], 12
	s_lshl_b64 s[18:19], s[18:19], 12
	s_lshl_b64 s[20:21], s[20:21], 12
	s_lshl_b64 s[24:25], s[24:25], 12
	s_lshl_b64 s[28:29], s[28:29], 12
	s_lshl_b64 s[30:31], s[30:31], 12
	s_lshl_b64 s[34:35], s[34:35], 12
	s_lshl_b64 s[36:37], s[36:37], 12
	s_lshl_b64 s[38:39], s[38:39], 12
	s_waitcnt lgkmcnt(0)
	v_lshl_add_u64 v[16:17], v[16:17], 2, s[6:7]
	s_lshl_b64 s[22:23], s[22:23], 12
	s_lshl_b64 s[26:27], s[26:27], 12
	s_lshl_b64 s[40:41], s[40:41], 12
	s_lshl_b64 s[42:43], s[42:43], 12
	s_lshl_b64 s[44:45], s[44:45], 12
	s_lshl_b64 s[46:47], s[46:47], 12
	s_lshl_b64 s[48:49], s[48:49], 12
	s_lshl_b64 s[50:51], s[50:51], 12
	s_lshl_b64 s[52:53], s[52:53], 12
	s_lshl_b64 s[54:55], s[54:55], 12
	s_lshl_b64 s[56:57], s[56:57], 12
	s_lshl_b64 s[58:59], s[58:59], 12
	s_lshl_b64 s[60:61], s[60:61], 12
	s_lshl_b64 s[68:69], s[68:69], 12
	s_lshl_b64 s[70:71], s[70:71], 12
	s_lshl_b64 s[72:73], s[72:73], 12
	s_lshl_b64 s[74:75], s[74:75], 12
	s_lshl_b64 s[76:77], s[76:77], 12
	s_lshl_b64 s[78:79], s[78:79], 12
	v_lshl_add_u64 v[18:19], v[16:17], 0, s[80:81]
	v_lshl_add_u64 v[20:21], v[16:17], 0, s[10:11]
	v_lshl_add_u64 v[22:23], v[16:17], 0, s[12:13]
	v_lshl_add_u64 v[24:25], v[16:17], 0, s[14:15]
	v_lshl_add_u64 v[26:27], v[16:17], 0, s[16:17]
	v_lshl_add_u64 v[28:29], v[16:17], 0, s[18:19]
	v_lshl_add_u64 v[30:31], v[16:17], 0, s[20:21]
	v_lshl_add_u64 v[34:35], v[16:17], 0, s[24:25]
	v_lshl_add_u64 v[38:39], v[16:17], 0, s[28:29]
	v_lshl_add_u64 v[40:41], v[16:17], 0, s[30:31]
	v_lshl_add_u64 v[42:43], v[16:17], 0, s[34:35]
	v_lshl_add_u64 v[44:45], v[16:17], 0, s[36:37]
	v_lshl_add_u64 v[46:47], v[16:17], 0, s[38:39]
	v_lshl_add_u64 v[32:33], v[16:17], 0, s[22:23]
	v_lshl_add_u64 v[36:37], v[16:17], 0, s[26:27]
	v_lshl_add_u64 v[48:49], v[16:17], 0, s[40:41]
	v_lshl_add_u64 v[50:51], v[16:17], 0, s[42:43]
	v_lshl_add_u64 v[52:53], v[16:17], 0, s[44:45]
	v_lshl_add_u64 v[54:55], v[16:17], 0, s[46:47]
	v_lshl_add_u64 v[56:57], v[16:17], 0, s[48:49]
	v_lshl_add_u64 v[58:59], v[16:17], 0, s[50:51]
	v_lshl_add_u64 v[60:61], v[16:17], 0, s[52:53]
	v_lshl_add_u64 v[62:63], v[16:17], 0, s[54:55]
	v_lshl_add_u64 v[64:65], v[16:17], 0, s[56:57]
	v_lshl_add_u64 v[66:67], v[16:17], 0, s[58:59]
	v_lshl_add_u64 v[68:69], v[16:17], 0, s[60:61]
	global_load_dword v70, v[18:19], off nt
	global_load_dword v71, v[20:21], off nt
	v_lshl_add_u64 v[18:19], v[16:17], 0, s[68:69]
	global_load_dword v72, v[22:23], off nt
	global_load_dword v73, v[24:25], off nt
	v_lshl_add_u64 v[20:21], v[16:17], 0, s[70:71]
	global_load_dword v74, v[26:27], off nt
	s_nop 0
	global_load_dword v28, v[28:29], off nt
	v_lshl_add_u64 v[22:23], v[16:17], 0, s[72:73]
	global_load_dword v29, v[30:31], off nt
	s_nop 0
	global_load_dword v30, v[32:33], off nt
	v_lshl_add_u64 v[24:25], v[16:17], 0, s[74:75]
	global_load_dword v31, v[34:35], off nt
	global_load_dword v75, v[36:37], off nt
	v_lshl_add_u64 v[26:27], v[16:17], 0, s[76:77]
	v_lshl_add_u64 v[16:17], v[16:17], 0, s[78:79]
	global_load_dword v76, v[38:39], off nt
	global_load_dword v77, v[40:41], off nt
	global_load_dword v78, v[42:43], off nt
	global_load_dword v79, v[44:45], off nt
	global_load_dword v80, v[46:47], off nt
	global_load_dword v81, v[48:49], off nt
	global_load_dword v82, v[50:51], off nt
	global_load_dword v83, v[52:53], off nt
	global_load_dword v84, v[54:55], off nt
	global_load_dword v85, v[56:57], off nt
	global_load_dword v86, v[58:59], off nt
	global_load_dword v87, v[60:61], off nt
	global_load_dword v88, v[62:63], off nt
	global_load_dword v89, v[64:65], off nt
	global_load_dword v90, v[66:67], off nt
	global_load_dword v40, v[68:69], off nt
	global_load_dword v41, v[18:19], off nt
	global_load_dword v42, v[20:21], off nt
	global_load_dword v43, v[22:23], off nt
	global_load_dword v44, v[24:25], off nt
	global_load_dword v45, v[26:27], off nt
	global_load_dword v46, v[16:17], off nt
	v_add_u32_e32 v18, s66, v5
	v_ashrrev_i32_e32 v19, 31, v18
	v_add_u32_e32 v20, 16, v18
	v_add_u32_e32 v22, 32, v18
	v_add_u32_e32 v24, 48, v18
	v_lshl_add_u64 v[16:17], s[8:9], 1, v[2:3]
	v_lshlrev_b64 v[18:19], 11, v[18:19]
	v_ashrrev_i32_e32 v21, 31, v20
	v_ashrrev_i32_e32 v23, 31, v22
	v_ashrrev_i32_e32 v25, 31, v24
	s_waitcnt vmcnt(30)
	ds_write2_b32 v4, v70, v71 offset1:65
	s_waitcnt vmcnt(28)
	ds_write2_b32 v4, v72, v73 offset0:130 offset1:195
	s_waitcnt vmcnt(26)
	ds_write2_b32 v8, v74, v28 offset0:4 offset1:69
	s_waitcnt vmcnt(24)
	ds_write2_b32 v8, v29, v30 offset0:134 offset1:199
	s_waitcnt vmcnt(22)
	ds_write2_b32 v9, v31, v75 offset0:8 offset1:73
	s_waitcnt vmcnt(20)
	ds_write2_b32 v9, v76, v77 offset0:138 offset1:203
	s_waitcnt vmcnt(18)
	ds_write2_b32 v10, v78, v79 offset0:12 offset1:77
	s_waitcnt vmcnt(16)
	ds_write2_b32 v10, v80, v81 offset0:142 offset1:207
	s_waitcnt vmcnt(14)
	ds_write2_b32 v11, v82, v83 offset0:16 offset1:81
	s_waitcnt vmcnt(12)
	ds_write2_b32 v11, v84, v85 offset0:146 offset1:211
	s_waitcnt vmcnt(10)
	ds_write2_b32 v12, v86, v87 offset0:20 offset1:85
	s_waitcnt vmcnt(8)
	ds_write2_b32 v12, v88, v89 offset0:150 offset1:215
	s_waitcnt vmcnt(6)
	ds_write2_b32 v13, v90, v40 offset0:24 offset1:89
	s_waitcnt vmcnt(4)
	ds_write2_b32 v13, v41, v42 offset0:154 offset1:219
	s_waitcnt vmcnt(2)
	ds_write2_b32 v14, v43, v44 offset0:28 offset1:93
	s_waitcnt vmcnt(0)
	ds_write2_b32 v14, v45, v46 offset0:158 offset1:223
	v_lshl_add_u64 v[32:33], v[16:17], 0, v[18:19]
	v_lshlrev_b64 v[18:19], 11, v[20:21]
	v_lshlrev_b64 v[20:21], 11, v[22:23]
	v_lshlrev_b64 v[22:23], 11, v[24:25]
	s_waitcnt lgkmcnt(0)
	v_lshl_add_u64 v[36:37], v[16:17], 0, v[20:21]
	v_lshl_add_u64 v[38:39], v[16:17], 0, v[22:23]
	ds_read2_b32 v[20:21], v6 offset1:16
	ds_read2_b32 v[22:23], v6 offset0:65 offset1:81
	ds_read2_b32 v[24:25], v6 offset0:130 offset1:146
	ds_read2_b32 v[26:27], v6 offset0:195 offset1:211
	ds_read2_b32 v[28:29], v15 offset0:4 offset1:20
	ds_read2_b32 v[30:31], v15 offset0:69 offset1:85
	ds_read2_b32 v[40:41], v15 offset0:134 offset1:150
	ds_read2_b32 v[42:43], v15 offset0:199 offset1:215
	ds_read2_b32 v[44:45], v6 offset0:32 offset1:48
	ds_read2_b32 v[46:47], v6 offset0:97 offset1:113
	ds_read2_b32 v[48:49], v6 offset0:162 offset1:178
	ds_read2_b32 v[50:51], v6 offset0:227 offset1:243
	ds_read2_b32 v[52:53], v15 offset0:36 offset1:52
	ds_read2_b32 v[54:55], v15 offset0:101 offset1:117
	ds_read2_b32 v[56:57], v15 offset0:166 offset1:182
	ds_read2_b32 v[58:59], v15 offset0:231 offset1:247
	v_lshl_add_u64 v[34:35], v[16:17], 0, v[18:19]
	s_waitcnt lgkmcnt(14)
	v_cvt_pk_bf16_f32 v16, v20, v22
	s_waitcnt lgkmcnt(12)
	v_cvt_pk_bf16_f32 v17, v24, v26
	s_waitcnt lgkmcnt(10)
	v_cvt_pk_bf16_f32 v18, v28, v30
	s_waitcnt lgkmcnt(8)
	v_cvt_pk_bf16_f32 v19, v40, v42
	v_cvt_pk_bf16_f32 v20, v21, v23
	v_cvt_pk_bf16_f32 v21, v25, v27
	v_cvt_pk_bf16_f32 v22, v29, v31
	v_cvt_pk_bf16_f32 v23, v41, v43
	s_waitcnt lgkmcnt(6)
	v_cvt_pk_bf16_f32 v24, v44, v46
	s_waitcnt lgkmcnt(4)
	v_cvt_pk_bf16_f32 v25, v48, v50
	s_waitcnt lgkmcnt(2)
	v_cvt_pk_bf16_f32 v26, v52, v54
	s_waitcnt lgkmcnt(0)
	v_cvt_pk_bf16_f32 v27, v56, v58
	v_cvt_pk_bf16_f32 v28, v45, v47
	v_cvt_pk_bf16_f32 v29, v49, v51
	v_cvt_pk_bf16_f32 v30, v53, v55
	v_cvt_pk_bf16_f32 v31, v57, v59
	global_store_dwordx4 v[32:33], v[16:19], off
	global_store_dwordx4 v[34:35], v[20:23], off
	global_store_dwordx4 v[36:37], v[24:27], off
	global_store_dwordx4 v[38:39], v[28:31], off
	s_waitcnt lgkmcnt(0)
	s_add_i32 s65, s65, s89
	s_add_i32 s63, s63, s64
	s_cmpk_lt_i32 s65, 0x200
	s_cbranch_scc1 .LBB0_14

.LBB0_379:
	s_mul_hi_i32 s12, s14, 0x2e8ba2e9
	s_lshr_b32 s13, s12, 31
	s_ashr_i32 s12, s12, 4
	s_add_i32 s13, s12, s13
	s_lshl_b32 s12, s13, 5
	s_mul_i32 s15, s13, 0xffffea00
	s_mulk_i32 s13, 0xf500
	s_bfe_i32 s18, s14, 0x10001
	s_add_i32 s13, s8, s13
	s_add_i32 s15, s6, s15
	s_and_b32 s18, s18, 0xb00
	s_and_b32 s13, s13, 0xffffff80
	s_add_i32 s18, s18, s13
	v_and_or_b32 v4, s15, 64, v1
	v_or3_b32 v4, s18, v4, v36
	v_ashrrev_i32_e32 v5, 31, v4
	v_lshl_add_u64 v[40:41], v[4:5], 2, s[0:1]
	s_or_b32 s13, s12, 1
	v_mad_i64_i32 v[4:5], s[18:19], s12, v247, v[40:41]
	v_mad_i64_i32 v[6:7], s[18:19], s13, v247, v[40:41]
	s_or_b32 s13, s12, 2
	global_load_dword v4, v[4:5], off nt
	s_andn2_b64 vcc, exec, s[10:11]
	global_load_dword v5, v[6:7], off nt
	v_mad_i64_i32 v[6:7], s[18:19], s13, v247, v[40:41]
	s_or_b32 s13, s12, 3
	v_mad_i64_i32 v[8:9], s[18:19], s13, v247, v[40:41]
	s_or_b32 s13, s12, 4
	global_load_dword v6, v[6:7], off nt
	s_nop 0
	global_load_dword v7, v[8:9], off nt
	v_mad_i64_i32 v[8:9], s[18:19], s13, v247, v[40:41]
	s_or_b32 s13, s12, 5
	v_mad_i64_i32 v[10:11], s[18:19], s13, v247, v[40:41]
	s_or_b32 s13, s12, 6
	global_load_dword v8, v[8:9], off nt
	s_nop 0
	global_load_dword v9, v[10:11], off nt
	v_mad_i64_i32 v[10:11], s[18:19], s13, v247, v[40:41]
	s_or_b32 s13, s12, 7
	v_mad_i64_i32 v[12:13], s[18:19], s13, v247, v[40:41]
	s_or_b32 s13, s12, 8
	global_load_dword v10, v[10:11], off nt
	s_nop 0
	global_load_dword v11, v[12:13], off nt
	v_mad_i64_i32 v[12:13], s[18:19], s13, v247, v[40:41]
	s_or_b32 s13, s12, 9
	v_mad_i64_i32 v[14:15], s[18:19], s13, v247, v[40:41]
	s_or_b32 s13, s12, 10
	global_load_dword v12, v[12:13], off nt
	s_nop 0
	global_load_dword v13, v[14:15], off nt
	v_mad_i64_i32 v[14:15], s[18:19], s13, v247, v[40:41]
	s_or_b32 s13, s12, 11
	v_mad_i64_i32 v[16:17], s[18:19], s13, v247, v[40:41]
	s_or_b32 s13, s12, 12
	global_load_dword v14, v[14:15], off nt
	s_nop 0
	global_load_dword v15, v[16:17], off nt
	v_mad_i64_i32 v[16:17], s[18:19], s13, v247, v[40:41]
	s_or_b32 s13, s12, 13
	v_mad_i64_i32 v[18:19], s[18:19], s13, v247, v[40:41]
	s_or_b32 s13, s12, 14
	global_load_dword v16, v[16:17], off nt
	s_nop 0
	global_load_dword v17, v[18:19], off nt
	v_mad_i64_i32 v[18:19], s[18:19], s13, v247, v[40:41]
	s_or_b32 s13, s12, 15
	v_mad_i64_i32 v[20:21], s[18:19], s13, v247, v[40:41]
	s_or_b32 s13, s12, 16
	global_load_dword v18, v[18:19], off nt
	s_nop 0
	global_load_dword v19, v[20:21], off nt
	v_mad_i64_i32 v[20:21], s[18:19], s13, v247, v[40:41]
	s_or_b32 s13, s12, 17
	v_mad_i64_i32 v[22:23], s[18:19], s13, v247, v[40:41]
	s_or_b32 s13, s12, 18
	global_load_dword v20, v[20:21], off nt
	s_nop 0
	global_load_dword v21, v[22:23], off nt
	v_mad_i64_i32 v[22:23], s[18:19], s13, v247, v[40:41]
	s_or_b32 s13, s12, 19
	v_mad_i64_i32 v[24:25], s[18:19], s13, v247, v[40:41]
	s_or_b32 s13, s12, 20
	global_load_dword v22, v[22:23], off nt
	s_nop 0
	global_load_dword v23, v[24:25], off nt
	v_mad_i64_i32 v[24:25], s[18:19], s13, v247, v[40:41]
	s_or_b32 s13, s12, 21
	v_mad_i64_i32 v[26:27], s[18:19], s13, v247, v[40:41]
	s_or_b32 s13, s12, 22
	global_load_dword v24, v[24:25], off nt
	s_nop 0
	global_load_dword v25, v[26:27], off nt
	v_mad_i64_i32 v[26:27], s[18:19], s13, v247, v[40:41]
	s_or_b32 s13, s12, 23
	v_mad_i64_i32 v[28:29], s[18:19], s13, v247, v[40:41]
	s_or_b32 s13, s12, 24
	global_load_dword v26, v[26:27], off nt
	s_nop 0
	global_load_dword v27, v[28:29], off nt
	v_mad_i64_i32 v[28:29], s[18:19], s13, v247, v[40:41]
	s_or_b32 s13, s12, 25
	v_mad_i64_i32 v[30:31], s[18:19], s13, v247, v[40:41]
	s_or_b32 s13, s12, 26
	global_load_dword v28, v[28:29], off nt
	s_nop 0
	global_load_dword v29, v[30:31], off nt
	v_mad_i64_i32 v[30:31], s[18:19], s13, v247, v[40:41]
	s_or_b32 s13, s12, 27
	v_mad_i64_i32 v[32:33], s[18:19], s13, v247, v[40:41]
	s_or_b32 s13, s12, 28
	global_load_dword v30, v[30:31], off nt
	s_nop 0
	global_load_dword v31, v[32:33], off nt
	v_mad_i64_i32 v[32:33], s[18:19], s13, v247, v[40:41]
	s_or_b32 s13, s12, 29
	v_mad_i64_i32 v[34:35], s[18:19], s13, v247, v[40:41]
	s_or_b32 s13, s12, 30
	global_load_dword v32, v[32:33], off nt
	s_nop 0
	global_load_dword v33, v[34:35], off nt
	v_mad_i64_i32 v[34:35], s[18:19], s13, v247, v[40:41]
	s_or_b32 s13, s12, 31
	v_mad_i64_i32 v[40:41], s[18:19], s13, v247, v[40:41]
	global_load_dword v34, v[34:35], off nt
	s_ashr_i32 s13, s12, 31
	global_load_dword v35, v[40:41], off nt
	s_cbranch_vccnz .LBB0_378
	s_lshl_b64 s[18:19], s[12:13], 2
	s_add_u32 s18, s4, s18
	s_addc_u32 s19, s5, s19
	global_load_dwordx4 v[40:43], v0, s[18:19]
	global_load_dwordx4 v[44:47], v0, s[18:19] offset:16
	global_load_dwordx4 v[48:51], v0, s[18:19] offset:32
	global_load_dwordx4 v[52:55], v0, s[18:19] offset:48
	global_load_dwordx4 v[56:59], v0, s[18:19] offset:64
	global_load_dwordx4 v[60:63], v0, s[18:19] offset:80
	global_load_dwordx4 v[64:67], v0, s[18:19] offset:96
	global_load_dwordx4 v[68:71], v0, s[18:19] offset:112
	s_waitcnt vmcnt(7)
	v_pk_mul_f32 v[4:5], v[4:5], v[40:41]
	v_pk_mul_f32 v[6:7], v[6:7], v[42:43]
	s_waitcnt vmcnt(6)
	v_pk_mul_f32 v[8:9], v[8:9], v[44:45]
	v_pk_mul_f32 v[10:11], v[10:11], v[46:47]
	s_waitcnt vmcnt(5)
	v_pk_mul_f32 v[12:13], v[12:13], v[48:49]
	v_pk_mul_f32 v[14:15], v[14:15], v[50:51]
	s_waitcnt vmcnt(4)
	v_pk_mul_f32 v[16:17], v[16:17], v[52:53]
	v_pk_mul_f32 v[18:19], v[18:19], v[54:55]
	s_waitcnt vmcnt(3)
	v_pk_mul_f32 v[20:21], v[20:21], v[56:57]
	v_pk_mul_f32 v[22:23], v[22:23], v[58:59]
	s_waitcnt vmcnt(2)
	v_pk_mul_f32 v[24:25], v[24:25], v[60:61]
	v_pk_mul_f32 v[26:27], v[26:27], v[62:63]
	s_waitcnt vmcnt(1)
	v_pk_mul_f32 v[28:29], v[28:29], v[64:65]
	v_pk_mul_f32 v[30:31], v[30:31], v[66:67]
	s_waitcnt vmcnt(0)
	v_pk_mul_f32 v[32:33], v[32:33], v[68:69]
	v_pk_mul_f32 v[34:35], v[34:35], v[70:71]
	s_branch .LBB0_378

.LBB0_384:
	s_ashr_i32 s7, s6, 31
	s_lshr_b32 s7, s7, 28
	s_add_i32 s7, s6, s7
	s_ashr_i32 s7, s7, 4
	s_lshl_b32 s10, s7, 5
	s_lshl_b32 s7, s7, 10
	s_sub_i32 s7, s4, s7
	v_add_u32_e32 v4, s7, v8
	v_ashrrev_i32_e32 v5, 31, v4
	s_ashr_i32 s11, s10, 31
	v_lshl_add_u64 v[4:5], v[4:5], 2, s[0:1]
	s_lshl_b64 s[8:9], s[10:11], 12
	v_lshl_add_u64 v[10:11], v[4:5], 0, s[8:9]
	s_or_b32 s8, s10, 1
	s_ashr_i32 s9, s8, 31
	s_lshl_b64 s[8:9], s[8:9], 12
	global_load_dword v9, v[10:11], off nt
	v_lshl_add_u64 v[10:11], v[4:5], 0, s[8:9]
	s_or_b32 s8, s10, 2
	s_ashr_i32 s9, s8, 31
	s_lshl_b64 s[8:9], s[8:9], 12
	v_lshl_add_u64 v[12:13], v[4:5], 0, s[8:9]
	s_or_b32 s8, s10, 3
	s_ashr_i32 s9, s8, 31
	s_lshl_b64 s[8:9], s[8:9], 12
	global_load_dword v10, v[10:11], off nt
	s_or_b32 s12, s10, 31
	global_load_dword v11, v[12:13], off nt
	v_lshl_add_u64 v[12:13], v[4:5], 0, s[8:9]
	s_or_b32 s8, s10, 4
	s_ashr_i32 s9, s8, 31
	s_lshl_b64 s[8:9], s[8:9], 12
	v_lshl_add_u64 v[14:15], v[4:5], 0, s[8:9]
	s_or_b32 s8, s10, 5
	s_ashr_i32 s9, s8, 31
	s_lshl_b64 s[8:9], s[8:9], 12
	global_load_dword v12, v[12:13], off nt
	s_ashr_i32 s13, s12, 31
	global_load_dword v13, v[14:15], off nt
	v_lshl_add_u64 v[14:15], v[4:5], 0, s[8:9]
	s_or_b32 s8, s10, 6
	s_ashr_i32 s9, s8, 31
	s_lshl_b64 s[8:9], s[8:9], 12
	v_lshl_add_u64 v[16:17], v[4:5], 0, s[8:9]
	s_or_b32 s8, s10, 7
	s_ashr_i32 s9, s8, 31
	s_lshl_b64 s[8:9], s[8:9], 12
	global_load_dword v14, v[14:15], off nt
	s_lshl_b64 s[12:13], s[12:13], 12
	global_load_dword v15, v[16:17], off nt
	v_lshl_add_u64 v[16:17], v[4:5], 0, s[8:9]
	s_or_b32 s8, s10, 8
	s_ashr_i32 s9, s8, 31
	s_lshl_b64 s[8:9], s[8:9], 12
	v_lshl_add_u64 v[18:19], v[4:5], 0, s[8:9]
	s_or_b32 s8, s10, 9
	s_ashr_i32 s9, s8, 31
	s_lshl_b64 s[8:9], s[8:9], 12
	global_load_dword v16, v[16:17], off nt
	s_add_i32 s6, s6, s89
	global_load_dword v17, v[18:19], off nt
	v_lshl_add_u64 v[18:19], v[4:5], 0, s[8:9]
	s_or_b32 s8, s10, 10
	s_ashr_i32 s9, s8, 31
	s_lshl_b64 s[8:9], s[8:9], 12
	v_lshl_add_u64 v[20:21], v[4:5], 0, s[8:9]
	s_or_b32 s8, s10, 11
	s_ashr_i32 s9, s8, 31
	s_lshl_b64 s[8:9], s[8:9], 12
	global_load_dword v18, v[18:19], off nt
	s_add_i32 s4, s4, s5
	global_load_dword v19, v[20:21], off nt
	v_lshl_add_u64 v[20:21], v[4:5], 0, s[8:9]
	s_or_b32 s8, s10, 12
	s_ashr_i32 s9, s8, 31
	s_lshl_b64 s[8:9], s[8:9], 12
	v_lshl_add_u64 v[22:23], v[4:5], 0, s[8:9]
	s_or_b32 s8, s10, 13
	s_ashr_i32 s9, s8, 31
	s_lshl_b64 s[8:9], s[8:9], 12
	global_load_dword v20, v[20:21], off nt
	s_nop 0
	global_load_dword v21, v[22:23], off nt
	v_lshl_add_u64 v[22:23], v[4:5], 0, s[8:9]
	s_or_b32 s8, s10, 14
	s_ashr_i32 s9, s8, 31
	s_lshl_b64 s[8:9], s[8:9], 12
	v_lshl_add_u64 v[24:25], v[4:5], 0, s[8:9]
	s_or_b32 s8, s10, 15
	s_ashr_i32 s9, s8, 31
	s_lshl_b64 s[8:9], s[8:9], 12
	global_load_dword v22, v[22:23], off nt
	s_nop 0
	global_load_dword v23, v[24:25], off nt
	v_lshl_add_u64 v[24:25], v[4:5], 0, s[8:9]
	s_or_b32 s8, s10, 16
	s_ashr_i32 s9, s8, 31
	s_lshl_b64 s[8:9], s[8:9], 12
	v_lshl_add_u64 v[26:27], v[4:5], 0, s[8:9]
	s_or_b32 s8, s10, 17
	s_ashr_i32 s9, s8, 31
	s_lshl_b64 s[8:9], s[8:9], 12
	global_load_dword v24, v[24:25], off nt
	s_nop 0
	global_load_dword v25, v[26:27], off nt
	v_lshl_add_u64 v[26:27], v[4:5], 0, s[8:9]
	s_or_b32 s8, s10, 18
	s_ashr_i32 s9, s8, 31
	s_lshl_b64 s[8:9], s[8:9], 12
	v_lshl_add_u64 v[28:29], v[4:5], 0, s[8:9]
	s_or_b32 s8, s10, 19
	s_ashr_i32 s9, s8, 31
	s_lshl_b64 s[8:9], s[8:9], 12
	global_load_dword v26, v[26:27], off nt
	s_nop 0
	global_load_dword v27, v[28:29], off nt
	v_lshl_add_u64 v[28:29], v[4:5], 0, s[8:9]
	s_or_b32 s8, s10, 20
	s_ashr_i32 s9, s8, 31
	s_lshl_b64 s[8:9], s[8:9], 12
	v_lshl_add_u64 v[30:31], v[4:5], 0, s[8:9]
	s_or_b32 s8, s10, 21
	s_ashr_i32 s9, s8, 31
	s_lshl_b64 s[8:9], s[8:9], 12
	global_load_dword v28, v[28:29], off nt
	s_nop 0
	global_load_dword v29, v[30:31], off nt
	v_lshl_add_u64 v[30:31], v[4:5], 0, s[8:9]
	s_or_b32 s8, s10, 22
	s_ashr_i32 s9, s8, 31
	s_lshl_b64 s[8:9], s[8:9], 12
	v_lshl_add_u64 v[32:33], v[4:5], 0, s[8:9]
	s_or_b32 s8, s10, 23
	s_ashr_i32 s9, s8, 31
	s_lshl_b64 s[8:9], s[8:9], 12
	global_load_dword v30, v[30:31], off nt
	s_nop 0
	global_load_dword v31, v[32:33], off nt
	v_lshl_add_u64 v[32:33], v[4:5], 0, s[8:9]
	s_or_b32 s8, s10, 24
	s_ashr_i32 s9, s8, 31
	s_lshl_b64 s[8:9], s[8:9], 12
	v_lshl_add_u64 v[34:35], v[4:5], 0, s[8:9]
	s_or_b32 s8, s10, 25
	s_ashr_i32 s9, s8, 31
	s_lshl_b64 s[8:9], s[8:9], 12
	global_load_dword v32, v[32:33], off nt
	s_nop 0
	global_load_dword v33, v[34:35], off nt
	v_lshl_add_u64 v[34:35], v[4:5], 0, s[8:9]
	s_or_b32 s8, s10, 26
	s_ashr_i32 s9, s8, 31
	s_lshl_b64 s[8:9], s[8:9], 12
	v_lshl_add_u64 v[36:37], v[4:5], 0, s[8:9]
	s_or_b32 s8, s10, 27
	s_ashr_i32 s9, s8, 31
	s_lshl_b64 s[8:9], s[8:9], 12
	global_load_dword v34, v[34:35], off nt
	s_nop 0
	global_load_dword v35, v[36:37], off nt
	v_lshl_add_u64 v[36:37], v[4:5], 0, s[8:9]
	s_or_b32 s8, s10, 28
	s_ashr_i32 s9, s8, 31
	s_lshl_b64 s[8:9], s[8:9], 12
	v_lshl_add_u64 v[38:39], v[4:5], 0, s[8:9]
	s_or_b32 s8, s10, 29
	s_ashr_i32 s9, s8, 31
	s_lshl_b64 s[8:9], s[8:9], 12
	global_load_dword v36, v[36:37], off nt
	s_nop 0
	global_load_dword v37, v[38:39], off nt
	v_lshl_add_u64 v[38:39], v[4:5], 0, s[8:9]
	s_or_b32 s8, s10, 30
	s_ashr_i32 s9, s8, 31
	s_lshl_b64 s[8:9], s[8:9], 12
	global_load_dword v38, v[38:39], off nt
	v_lshl_add_u64 v[40:41], v[4:5], 0, s[8:9]
	v_lshl_add_u64 v[4:5], v[4:5], 0, s[12:13]
	global_load_dword v4, v[4:5], off nt
	v_add_u32_e32 v5, 0x400, v1
	global_load_dword v39, v[40:41], off nt
	s_waitcnt vmcnt(30)
	ds_write2_b32 v1, v9, v10 offset1:65
	s_waitcnt vmcnt(28)
	ds_write2_b32 v1, v11, v12 offset0:130 offset1:195
	s_waitcnt vmcnt(26)
	ds_write2_b32 v5, v13, v14 offset0:4 offset1:69
	s_waitcnt vmcnt(24)
	ds_write2_b32 v5, v15, v16 offset0:134 offset1:199
	v_add_u32_e32 v5, 0x800, v1
	s_waitcnt vmcnt(22)
	ds_write2_b32 v5, v17, v18 offset0:8 offset1:73
	s_waitcnt vmcnt(20)
	ds_write2_b32 v5, v19, v20 offset0:138 offset1:203
	v_add_u32_e32 v5, 0xc00, v1
	s_waitcnt vmcnt(18)
	ds_write2_b32 v5, v21, v22 offset0:12 offset1:77
	s_waitcnt vmcnt(16)
	ds_write2_b32 v5, v23, v24 offset0:142 offset1:207
	v_add_u32_e32 v5, 0x1000, v1
	s_waitcnt vmcnt(14)
	ds_write2_b32 v5, v25, v26 offset0:16 offset1:81
	s_waitcnt vmcnt(12)
	ds_write2_b32 v5, v27, v28 offset0:146 offset1:211
	v_add_u32_e32 v5, 0x1400, v1
	s_waitcnt vmcnt(10)
	ds_write2_b32 v5, v29, v30 offset0:20 offset1:85
	s_waitcnt vmcnt(8)
	ds_write2_b32 v5, v31, v32 offset0:150 offset1:215
	v_add_u32_e32 v5, 0x1800, v1
	s_waitcnt vmcnt(6)
	ds_write2_b32 v5, v33, v34 offset0:24 offset1:89
	s_waitcnt vmcnt(4)
	ds_write2_b32 v5, v35, v36 offset0:154 offset1:219
	v_add_u32_e32 v5, 0x1c00, v1
	s_waitcnt vmcnt(2)
	ds_write2_b32 v5, v37, v38 offset0:28 offset1:93
	s_waitcnt vmcnt(0)
	ds_write2_b32 v5, v39, v4 offset0:158 offset1:223
	s_waitcnt lgkmcnt(0)
	v_add_u32_e32 v9, 0x400, v7
	ds_read2_b32 v[14:15], v7 offset1:16
	ds_read2_b32 v[16:17], v7 offset0:65 offset1:81
	ds_read2_b32 v[18:19], v7 offset0:130 offset1:146
	ds_read2_b32 v[20:21], v7 offset0:195 offset1:211
	ds_read2_b32 v[22:23], v9 offset0:4 offset1:20
	ds_read2_b32 v[24:25], v9 offset0:69 offset1:85
	ds_read2_b32 v[26:27], v9 offset0:134 offset1:150
	ds_read2_b32 v[28:29], v9 offset0:199 offset1:215
	v_lshl_add_u64 v[4:5], s[10:11], 1, v[2:3]
	v_add_u32_e32 v32, s7, v6
	s_waitcnt lgkmcnt(6)
	v_cvt_pk_bf16_f32 v10, v14, v16
	s_waitcnt lgkmcnt(4)
	v_cvt_pk_bf16_f32 v11, v18, v20
	s_waitcnt lgkmcnt(2)
	v_cvt_pk_bf16_f32 v12, v22, v24
	s_waitcnt lgkmcnt(0)
	v_cvt_pk_bf16_f32 v13, v26, v28
	v_mad_i64_i32 v[30:31], s[8:9], v32, s54, v[4:5]
	v_add_u32_e32 v14, 16, v32
	global_store_dwordx4 v[30:31], v[10:13], off
	s_cmpk_lt_i32 s6, 0x580
	s_nop 0
	v_cvt_pk_bf16_f32 v10, v15, v17
	v_cvt_pk_bf16_f32 v11, v19, v21
	v_cvt_pk_bf16_f32 v12, v23, v25
	v_cvt_pk_bf16_f32 v13, v27, v29
	v_mad_i64_i32 v[14:15], s[8:9], v14, s54, v[4:5]
	global_store_dwordx4 v[14:15], v[10:13], off
	ds_read2_b32 v[14:15], v7 offset0:32 offset1:48
	ds_read2_b32 v[16:17], v7 offset0:97 offset1:113
	ds_read2_b32 v[18:19], v7 offset0:162 offset1:178
	ds_read2_b32 v[20:21], v7 offset0:227 offset1:243
	ds_read2_b32 v[22:23], v9 offset0:36 offset1:52
	ds_read2_b32 v[24:25], v9 offset0:101 offset1:117
	ds_read2_b32 v[26:27], v9 offset0:166 offset1:182
	ds_read2_b32 v[28:29], v9 offset0:231 offset1:247
	v_add_u32_e32 v9, 32, v32
	s_waitcnt lgkmcnt(6)
	v_cvt_pk_bf16_f32 v10, v14, v16
	s_waitcnt lgkmcnt(4)
	v_cvt_pk_bf16_f32 v11, v18, v20
	s_waitcnt lgkmcnt(2)
	v_cvt_pk_bf16_f32 v12, v22, v24
	s_waitcnt lgkmcnt(0)
	v_cvt_pk_bf16_f32 v13, v26, v28
	v_mad_i64_i32 v[30:31], s[8:9], v9, s54, v[4:5]
	v_add_u32_e32 v9, 48, v32
	global_store_dwordx4 v[30:31], v[10:13], off
	v_mad_i64_i32 v[4:5], s[8:9], v9, s54, v[4:5]
	s_nop 0
	v_cvt_pk_bf16_f32 v10, v15, v17
	v_cvt_pk_bf16_f32 v11, v19, v21
	v_cvt_pk_bf16_f32 v12, v23, v25
	v_cvt_pk_bf16_f32 v13, v27, v29
	global_store_dwordx4 v[4:5], v[10:13], off
	s_waitcnt lgkmcnt(0)
	s_cbranch_scc1 .LBB0_384

.LBB0_388:
	s_ashr_i32 s9, s8, 31
	s_lshr_b32 s9, s9, 28
	s_add_i32 s9, s8, s9
	s_ashr_i32 s9, s9, 4
	s_lshl_b32 s12, s9, 5
	s_lshl_b32 s9, s9, 10
	s_sub_i32 s13, s6, s9
	v_add_u32_e32 v4, s13, v40
	v_ashrrev_i32_e32 v5, 31, v4
	s_ashr_i32 s13, s12, 31
	v_lshl_add_u64 v[26:27], v[4:5], 2, s[0:1]
	s_lshl_b64 s[14:15], s[12:13], 12
	v_lshl_add_u64 v[4:5], v[26:27], 0, s[14:15]
	s_or_b32 s14, s12, 1
	s_ashr_i32 s15, s14, 31
	s_lshl_b64 s[14:15], s[14:15], 12
	v_lshl_add_u64 v[6:7], v[26:27], 0, s[14:15]
	s_or_b32 s14, s12, 2
	s_ashr_i32 s15, s14, 31
	s_lshl_b64 s[14:15], s[14:15], 12
	global_load_dword v4, v[4:5], off nt
	s_andn2_b64 vcc, exec, s[10:11]
	global_load_dword v5, v[6:7], off nt
	v_lshl_add_u64 v[6:7], v[26:27], 0, s[14:15]
	s_or_b32 s14, s12, 3
	s_ashr_i32 s15, s14, 31
	s_lshl_b64 s[14:15], s[14:15], 12
	v_lshl_add_u64 v[8:9], v[26:27], 0, s[14:15]
	s_or_b32 s14, s12, 4
	s_ashr_i32 s15, s14, 31
	s_lshl_b64 s[14:15], s[14:15], 12
	global_load_dword v6, v[6:7], off nt
	s_nop 0
	global_load_dword v7, v[8:9], off nt
	v_lshl_add_u64 v[8:9], v[26:27], 0, s[14:15]
	s_or_b32 s14, s12, 5
	s_ashr_i32 s15, s14, 31
	s_lshl_b64 s[14:15], s[14:15], 12
	v_lshl_add_u64 v[10:11], v[26:27], 0, s[14:15]
	s_or_b32 s14, s12, 6
	s_ashr_i32 s15, s14, 31
	s_lshl_b64 s[14:15], s[14:15], 12
	global_load_dword v8, v[8:9], off nt
	s_nop 0
	global_load_dword v9, v[10:11], off nt
	v_lshl_add_u64 v[10:11], v[26:27], 0, s[14:15]
	s_or_b32 s14, s12, 7
	s_ashr_i32 s15, s14, 31
	s_lshl_b64 s[14:15], s[14:15], 12
	v_lshl_add_u64 v[12:13], v[26:27], 0, s[14:15]
	s_or_b32 s14, s12, 8
	s_ashr_i32 s15, s14, 31
	s_lshl_b64 s[14:15], s[14:15], 12
	global_load_dword v10, v[10:11], off nt
	s_nop 0
	global_load_dword v11, v[12:13], off nt
	v_lshl_add_u64 v[12:13], v[26:27], 0, s[14:15]
	s_or_b32 s14, s12, 9
	s_ashr_i32 s15, s14, 31
	s_lshl_b64 s[14:15], s[14:15], 12
	v_lshl_add_u64 v[14:15], v[26:27], 0, s[14:15]
	s_or_b32 s14, s12, 10
	s_ashr_i32 s15, s14, 31
	s_lshl_b64 s[14:15], s[14:15], 12
	global_load_dword v12, v[12:13], off nt
	s_nop 0
	global_load_dword v13, v[14:15], off nt
	v_lshl_add_u64 v[14:15], v[26:27], 0, s[14:15]
	s_or_b32 s14, s12, 11
	s_ashr_i32 s15, s14, 31
	s_lshl_b64 s[14:15], s[14:15], 12
	v_lshl_add_u64 v[16:17], v[26:27], 0, s[14:15]
	s_or_b32 s14, s12, 12
	s_ashr_i32 s15, s14, 31
	s_lshl_b64 s[14:15], s[14:15], 12
	global_load_dword v14, v[14:15], off nt
	s_nop 0
	global_load_dword v15, v[16:17], off nt
	v_lshl_add_u64 v[16:17], v[26:27], 0, s[14:15]
	s_or_b32 s14, s12, 13
	s_ashr_i32 s15, s14, 31
	s_lshl_b64 s[14:15], s[14:15], 12
	v_lshl_add_u64 v[18:19], v[26:27], 0, s[14:15]
	s_or_b32 s14, s12, 14
	s_ashr_i32 s15, s14, 31
	s_lshl_b64 s[14:15], s[14:15], 12
	global_load_dword v16, v[16:17], off nt
	s_nop 0
	global_load_dword v17, v[18:19], off nt
	v_lshl_add_u64 v[18:19], v[26:27], 0, s[14:15]
	s_or_b32 s14, s12, 15
	s_ashr_i32 s15, s14, 31
	s_lshl_b64 s[14:15], s[14:15], 12
	v_lshl_add_u64 v[20:21], v[26:27], 0, s[14:15]
	s_or_b32 s14, s12, 16
	s_ashr_i32 s15, s14, 31
	s_lshl_b64 s[14:15], s[14:15], 12
	global_load_dword v18, v[18:19], off nt
	s_nop 0
	global_load_dword v19, v[20:21], off nt
	v_lshl_add_u64 v[20:21], v[26:27], 0, s[14:15]
	s_or_b32 s14, s12, 17
	s_ashr_i32 s15, s14, 31
	s_lshl_b64 s[14:15], s[14:15], 12
	v_lshl_add_u64 v[22:23], v[26:27], 0, s[14:15]
	s_or_b32 s14, s12, 18
	s_ashr_i32 s15, s14, 31
	s_lshl_b64 s[14:15], s[14:15], 12
	global_load_dword v20, v[20:21], off nt
	s_nop 0
	global_load_dword v21, v[22:23], off nt
	v_lshl_add_u64 v[22:23], v[26:27], 0, s[14:15]
	s_or_b32 s14, s12, 19
	s_ashr_i32 s15, s14, 31
	s_lshl_b64 s[14:15], s[14:15], 12
	v_lshl_add_u64 v[24:25], v[26:27], 0, s[14:15]
	s_or_b32 s14, s12, 20
	s_ashr_i32 s15, s14, 31
	s_lshl_b64 s[14:15], s[14:15], 12
	global_load_dword v22, v[22:23], off nt
	s_nop 0
	global_load_dword v23, v[24:25], off nt
	v_lshl_add_u64 v[24:25], v[26:27], 0, s[14:15]
	s_or_b32 s14, s12, 21
	s_ashr_i32 s15, s14, 31
	s_lshl_b64 s[14:15], s[14:15], 12
	v_lshl_add_u64 v[28:29], v[26:27], 0, s[14:15]
	s_or_b32 s14, s12, 22
	s_ashr_i32 s15, s14, 31
	s_lshl_b64 s[14:15], s[14:15], 12
	global_load_dword v24, v[24:25], off nt
	s_nop 0
	global_load_dword v25, v[28:29], off nt
	v_lshl_add_u64 v[28:29], v[26:27], 0, s[14:15]
	s_or_b32 s14, s12, 23
	s_ashr_i32 s15, s14, 31
	s_lshl_b64 s[14:15], s[14:15], 12
	v_lshl_add_u64 v[30:31], v[26:27], 0, s[14:15]
	s_or_b32 s14, s12, 24
	s_ashr_i32 s15, s14, 31
	s_lshl_b64 s[14:15], s[14:15], 12
	global_load_dword v28, v[28:29], off nt
	s_nop 0
	global_load_dword v29, v[30:31], off nt
	v_lshl_add_u64 v[30:31], v[26:27], 0, s[14:15]
	s_or_b32 s14, s12, 25
	s_ashr_i32 s15, s14, 31
	s_lshl_b64 s[14:15], s[14:15], 12
	v_lshl_add_u64 v[32:33], v[26:27], 0, s[14:15]
	s_or_b32 s14, s12, 26
	s_ashr_i32 s15, s14, 31
	s_lshl_b64 s[14:15], s[14:15], 12
	global_load_dword v30, v[30:31], off nt
	s_nop 0
	global_load_dword v31, v[32:33], off nt
	v_lshl_add_u64 v[32:33], v[26:27], 0, s[14:15]
	s_or_b32 s14, s12, 27
	s_ashr_i32 s15, s14, 31
	s_lshl_b64 s[14:15], s[14:15], 12
	v_lshl_add_u64 v[34:35], v[26:27], 0, s[14:15]
	s_or_b32 s14, s12, 28
	s_ashr_i32 s15, s14, 31
	s_lshl_b64 s[14:15], s[14:15], 12
	global_load_dword v32, v[32:33], off nt
	s_nop 0
	global_load_dword v33, v[34:35], off nt
	v_lshl_add_u64 v[34:35], v[26:27], 0, s[14:15]
	s_or_b32 s14, s12, 29
	s_ashr_i32 s15, s14, 31
	s_lshl_b64 s[14:15], s[14:15], 12
	v_lshl_add_u64 v[36:37], v[26:27], 0, s[14:15]
	s_or_b32 s14, s12, 30
	s_ashr_i32 s15, s14, 31
	s_lshl_b64 s[14:15], s[14:15], 12
	global_load_dword v34, v[34:35], off nt
	s_nop 0
	global_load_dword v35, v[36:37], off nt
	v_lshl_add_u64 v[36:37], v[26:27], 0, s[14:15]
	s_or_b32 s14, s12, 31
	s_ashr_i32 s15, s14, 31
	s_lshl_b64 s[14:15], s[14:15], 12
	v_lshl_add_u64 v[26:27], v[26:27], 0, s[14:15]
	global_load_dword v36, v[36:37], off nt
	s_nop 0
	global_load_dword v37, v[26:27], off nt
	s_cbranch_vccnz .LBB0_387
	s_lshl_b64 s[14:15], s[12:13], 2
	s_add_u32 s14, s4, s14
	s_addc_u32 s15, s5, s15
	global_load_dwordx4 v[42:45], v0, s[14:15]
	global_load_dwordx4 v[46:49], v0, s[14:15] offset:16
	global_load_dwordx4 v[50:53], v0, s[14:15] offset:32
	global_load_dwordx4 v[54:57], v0, s[14:15] offset:48
	global_load_dwordx4 v[58:61], v0, s[14:15] offset:64
	global_load_dwordx4 v[62:65], v0, s[14:15] offset:80
	global_load_dwordx4 v[66:69], v0, s[14:15] offset:96
	global_load_dwordx4 v[70:73], v0, s[14:15] offset:112
	s_waitcnt vmcnt(7)
	v_pk_mul_f32 v[4:5], v[4:5], v[42:43]
	v_pk_mul_f32 v[6:7], v[6:7], v[44:45]
	s_waitcnt vmcnt(6)
	v_pk_mul_f32 v[8:9], v[8:9], v[46:47]
	v_pk_mul_f32 v[10:11], v[10:11], v[48:49]
	s_waitcnt vmcnt(5)
	v_pk_mul_f32 v[12:13], v[12:13], v[50:51]
	v_pk_mul_f32 v[14:15], v[14:15], v[52:53]
	s_waitcnt vmcnt(4)
	v_pk_mul_f32 v[16:17], v[16:17], v[54:55]
	v_pk_mul_f32 v[18:19], v[18:19], v[56:57]
	s_waitcnt vmcnt(3)
	v_pk_mul_f32 v[20:21], v[20:21], v[58:59]
	v_pk_mul_f32 v[22:23], v[22:23], v[60:61]
	s_waitcnt vmcnt(2)
	v_pk_mul_f32 v[24:25], v[24:25], v[62:63]
	v_pk_mul_f32 v[28:29], v[28:29], v[64:65]
	s_waitcnt vmcnt(1)
	v_pk_mul_f32 v[30:31], v[30:31], v[66:67]
	v_pk_mul_f32 v[32:33], v[32:33], v[68:69]
	s_waitcnt vmcnt(0)
	v_pk_mul_f32 v[34:35], v[34:35], v[70:71]
	v_pk_mul_f32 v[36:37], v[36:37], v[72:73]
	s_branch .LBB0_387

.LBB0_392:
	s_ashr_i32 s7, s6, 31
	s_lshr_b32 s7, s7, 28
	s_add_i32 s7, s6, s7
	s_ashr_i32 s7, s7, 4
	s_lshl_b32 s10, s7, 5
	s_lshl_b32 s7, s7, 10
	s_sub_i32 s7, s4, s7
	v_add_u32_e32 v4, s7, v8
	v_ashrrev_i32_e32 v5, 31, v4
	s_ashr_i32 s11, s10, 31
	v_lshl_add_u64 v[4:5], v[4:5], 2, s[0:1]
	s_lshl_b64 s[8:9], s[10:11], 12
	v_lshl_add_u64 v[10:11], v[4:5], 0, s[8:9]
	s_or_b32 s8, s10, 1
	s_ashr_i32 s9, s8, 31
	s_lshl_b64 s[8:9], s[8:9], 12
	global_load_dword v9, v[10:11], off nt
	v_lshl_add_u64 v[10:11], v[4:5], 0, s[8:9]
	s_or_b32 s8, s10, 2
	s_ashr_i32 s9, s8, 31
	s_lshl_b64 s[8:9], s[8:9], 12
	v_lshl_add_u64 v[12:13], v[4:5], 0, s[8:9]
	s_or_b32 s8, s10, 3
	s_ashr_i32 s9, s8, 31
	s_lshl_b64 s[8:9], s[8:9], 12
	global_load_dword v10, v[10:11], off nt
	s_or_b32 s12, s10, 31
	global_load_dword v11, v[12:13], off nt
	v_lshl_add_u64 v[12:13], v[4:5], 0, s[8:9]
	s_or_b32 s8, s10, 4
	s_ashr_i32 s9, s8, 31
	s_lshl_b64 s[8:9], s[8:9], 12
	v_lshl_add_u64 v[14:15], v[4:5], 0, s[8:9]
	s_or_b32 s8, s10, 5
	s_ashr_i32 s9, s8, 31
	s_lshl_b64 s[8:9], s[8:9], 12
	global_load_dword v12, v[12:13], off nt
	s_ashr_i32 s13, s12, 31
	global_load_dword v13, v[14:15], off nt
	v_lshl_add_u64 v[14:15], v[4:5], 0, s[8:9]
	s_or_b32 s8, s10, 6
	s_ashr_i32 s9, s8, 31
	s_lshl_b64 s[8:9], s[8:9], 12
	v_lshl_add_u64 v[16:17], v[4:5], 0, s[8:9]
	s_or_b32 s8, s10, 7
	s_ashr_i32 s9, s8, 31
	s_lshl_b64 s[8:9], s[8:9], 12
	global_load_dword v14, v[14:15], off nt
	s_lshl_b64 s[12:13], s[12:13], 12
	global_load_dword v15, v[16:17], off nt
	v_lshl_add_u64 v[16:17], v[4:5], 0, s[8:9]
	s_or_b32 s8, s10, 8
	s_ashr_i32 s9, s8, 31
	s_lshl_b64 s[8:9], s[8:9], 12
	v_lshl_add_u64 v[18:19], v[4:5], 0, s[8:9]
	s_or_b32 s8, s10, 9
	s_ashr_i32 s9, s8, 31
	s_lshl_b64 s[8:9], s[8:9], 12
	global_load_dword v16, v[16:17], off nt
	s_add_i32 s6, s6, s89
	global_load_dword v17, v[18:19], off nt
	v_lshl_add_u64 v[18:19], v[4:5], 0, s[8:9]
	s_or_b32 s8, s10, 10
	s_ashr_i32 s9, s8, 31
	s_lshl_b64 s[8:9], s[8:9], 12
	v_lshl_add_u64 v[20:21], v[4:5], 0, s[8:9]
	s_or_b32 s8, s10, 11
	s_ashr_i32 s9, s8, 31
	s_lshl_b64 s[8:9], s[8:9], 12
	global_load_dword v18, v[18:19], off nt
	s_add_i32 s4, s4, s5
	global_load_dword v19, v[20:21], off nt
	v_lshl_add_u64 v[20:21], v[4:5], 0, s[8:9]
	s_or_b32 s8, s10, 12
	s_ashr_i32 s9, s8, 31
	s_lshl_b64 s[8:9], s[8:9], 12
	v_lshl_add_u64 v[22:23], v[4:5], 0, s[8:9]
	s_or_b32 s8, s10, 13
	s_ashr_i32 s9, s8, 31
	s_lshl_b64 s[8:9], s[8:9], 12
	global_load_dword v20, v[20:21], off nt
	s_nop 0
	global_load_dword v21, v[22:23], off nt
	v_lshl_add_u64 v[22:23], v[4:5], 0, s[8:9]
	s_or_b32 s8, s10, 14
	s_ashr_i32 s9, s8, 31
	s_lshl_b64 s[8:9], s[8:9], 12
	v_lshl_add_u64 v[24:25], v[4:5], 0, s[8:9]
	s_or_b32 s8, s10, 15
	s_ashr_i32 s9, s8, 31
	s_lshl_b64 s[8:9], s[8:9], 12
	global_load_dword v22, v[22:23], off nt
	s_nop 0
	global_load_dword v23, v[24:25], off nt
	v_lshl_add_u64 v[24:25], v[4:5], 0, s[8:9]
	s_or_b32 s8, s10, 16
	s_ashr_i32 s9, s8, 31
	s_lshl_b64 s[8:9], s[8:9], 12
	v_lshl_add_u64 v[26:27], v[4:5], 0, s[8:9]
	s_or_b32 s8, s10, 17
	s_ashr_i32 s9, s8, 31
	s_lshl_b64 s[8:9], s[8:9], 12
	global_load_dword v24, v[24:25], off nt
	s_nop 0
	global_load_dword v25, v[26:27], off nt
	v_lshl_add_u64 v[26:27], v[4:5], 0, s[8:9]
	s_or_b32 s8, s10, 18
	s_ashr_i32 s9, s8, 31
	s_lshl_b64 s[8:9], s[8:9], 12
	v_lshl_add_u64 v[28:29], v[4:5], 0, s[8:9]
	s_or_b32 s8, s10, 19
	s_ashr_i32 s9, s8, 31
	s_lshl_b64 s[8:9], s[8:9], 12
	global_load_dword v26, v[26:27], off nt
	s_nop 0
	global_load_dword v27, v[28:29], off nt
	v_lshl_add_u64 v[28:29], v[4:5], 0, s[8:9]
	s_or_b32 s8, s10, 20
	s_ashr_i32 s9, s8, 31
	s_lshl_b64 s[8:9], s[8:9], 12
	v_lshl_add_u64 v[30:31], v[4:5], 0, s[8:9]
	s_or_b32 s8, s10, 21
	s_ashr_i32 s9, s8, 31
	s_lshl_b64 s[8:9], s[8:9], 12
	global_load_dword v28, v[28:29], off nt
	s_nop 0
	global_load_dword v29, v[30:31], off nt
	v_lshl_add_u64 v[30:31], v[4:5], 0, s[8:9]
	s_or_b32 s8, s10, 22
	s_ashr_i32 s9, s8, 31
	s_lshl_b64 s[8:9], s[8:9], 12
	v_lshl_add_u64 v[32:33], v[4:5], 0, s[8:9]
	s_or_b32 s8, s10, 23
	s_ashr_i32 s9, s8, 31
	s_lshl_b64 s[8:9], s[8:9], 12
	global_load_dword v30, v[30:31], off nt
	s_nop 0
	global_load_dword v31, v[32:33], off nt
	v_lshl_add_u64 v[32:33], v[4:5], 0, s[8:9]
	s_or_b32 s8, s10, 24
	s_ashr_i32 s9, s8, 31
	s_lshl_b64 s[8:9], s[8:9], 12
	v_lshl_add_u64 v[34:35], v[4:5], 0, s[8:9]
	s_or_b32 s8, s10, 25
	s_ashr_i32 s9, s8, 31
	s_lshl_b64 s[8:9], s[8:9], 12
	global_load_dword v32, v[32:33], off nt
	s_nop 0
	global_load_dword v33, v[34:35], off nt
	v_lshl_add_u64 v[34:35], v[4:5], 0, s[8:9]
	s_or_b32 s8, s10, 26
	s_ashr_i32 s9, s8, 31
	s_lshl_b64 s[8:9], s[8:9], 12
	v_lshl_add_u64 v[36:37], v[4:5], 0, s[8:9]
	s_or_b32 s8, s10, 27
	s_ashr_i32 s9, s8, 31
	s_lshl_b64 s[8:9], s[8:9], 12
	global_load_dword v34, v[34:35], off nt
	s_nop 0
	global_load_dword v35, v[36:37], off nt
	v_lshl_add_u64 v[36:37], v[4:5], 0, s[8:9]
	s_or_b32 s8, s10, 28
	s_ashr_i32 s9, s8, 31
	s_lshl_b64 s[8:9], s[8:9], 12
	v_lshl_add_u64 v[38:39], v[4:5], 0, s[8:9]
	s_or_b32 s8, s10, 29
	s_ashr_i32 s9, s8, 31
	s_lshl_b64 s[8:9], s[8:9], 12
	global_load_dword v36, v[36:37], off nt
	s_nop 0
	global_load_dword v37, v[38:39], off nt
	v_lshl_add_u64 v[38:39], v[4:5], 0, s[8:9]
	s_or_b32 s8, s10, 30
	s_ashr_i32 s9, s8, 31
	s_lshl_b64 s[8:9], s[8:9], 12
	global_load_dword v38, v[38:39], off nt
	v_lshl_add_u64 v[40:41], v[4:5], 0, s[8:9]
	v_lshl_add_u64 v[4:5], v[4:5], 0, s[12:13]
	global_load_dword v4, v[4:5], off nt
	v_add_u32_e32 v5, 0x400, v1
	global_load_dword v39, v[40:41], off nt
	s_waitcnt vmcnt(30)
	ds_write2_b32 v1, v9, v10 offset1:65
	s_waitcnt vmcnt(28)
	ds_write2_b32 v1, v11, v12 offset0:130 offset1:195
	s_waitcnt vmcnt(26)
	ds_write2_b32 v5, v13, v14 offset0:4 offset1:69
	s_waitcnt vmcnt(24)
	ds_write2_b32 v5, v15, v16 offset0:134 offset1:199
	v_add_u32_e32 v5, 0x800, v1
	s_waitcnt vmcnt(22)
	ds_write2_b32 v5, v17, v18 offset0:8 offset1:73
	s_waitcnt vmcnt(20)
	ds_write2_b32 v5, v19, v20 offset0:138 offset1:203
	v_add_u32_e32 v5, 0xc00, v1
	s_waitcnt vmcnt(18)
	ds_write2_b32 v5, v21, v22 offset0:12 offset1:77
	s_waitcnt vmcnt(16)
	ds_write2_b32 v5, v23, v24 offset0:142 offset1:207
	v_add_u32_e32 v5, 0x1000, v1
	s_waitcnt vmcnt(14)
	ds_write2_b32 v5, v25, v26 offset0:16 offset1:81
	s_waitcnt vmcnt(12)
	ds_write2_b32 v5, v27, v28 offset0:146 offset1:211
	v_add_u32_e32 v5, 0x1400, v1
	s_waitcnt vmcnt(10)
	ds_write2_b32 v5, v29, v30 offset0:20 offset1:85
	s_waitcnt vmcnt(8)
	ds_write2_b32 v5, v31, v32 offset0:150 offset1:215
	v_add_u32_e32 v5, 0x1800, v1
	s_waitcnt vmcnt(6)
	ds_write2_b32 v5, v33, v34 offset0:24 offset1:89
	s_waitcnt vmcnt(4)
	ds_write2_b32 v5, v35, v36 offset0:154 offset1:219
	v_add_u32_e32 v5, 0x1c00, v1
	s_waitcnt vmcnt(2)
	ds_write2_b32 v5, v37, v38 offset0:28 offset1:93
	s_waitcnt vmcnt(0)
	ds_write2_b32 v5, v39, v4 offset0:158 offset1:223
	s_waitcnt lgkmcnt(0)
	v_add_u32_e32 v9, 0x400, v7
	ds_read2_b32 v[14:15], v7 offset1:16
	ds_read2_b32 v[16:17], v7 offset0:65 offset1:81
	ds_read2_b32 v[18:19], v7 offset0:130 offset1:146
	ds_read2_b32 v[20:21], v7 offset0:195 offset1:211
	ds_read2_b32 v[22:23], v9 offset0:4 offset1:20
	ds_read2_b32 v[24:25], v9 offset0:69 offset1:85
	ds_read2_b32 v[26:27], v9 offset0:134 offset1:150
	ds_read2_b32 v[28:29], v9 offset0:199 offset1:215
	v_add_u32_e32 v30, s7, v6
	v_ashrrev_i32_e32 v31, 31, v30
	v_lshl_add_u64 v[4:5], s[10:11], 1, v[2:3]
	v_lshlrev_b64 v[32:33], 9, v[30:31]
	s_waitcnt lgkmcnt(6)
	v_cvt_pk_bf16_f32 v10, v14, v16
	s_waitcnt lgkmcnt(4)
	v_cvt_pk_bf16_f32 v11, v18, v20
	s_waitcnt lgkmcnt(2)
	v_cvt_pk_bf16_f32 v12, v22, v24
	s_waitcnt lgkmcnt(0)
	v_cvt_pk_bf16_f32 v13, v26, v28
	v_lshl_add_u64 v[32:33], v[4:5], 0, v[32:33]
	v_add_u32_e32 v14, 16, v30
	global_store_dwordx4 v[32:33], v[10:13], off
	v_add_u32_e32 v32, 32, v30
	v_ashrrev_i32_e32 v33, 31, v32
	v_cvt_pk_bf16_f32 v10, v15, v17
	v_ashrrev_i32_e32 v15, 31, v14
	v_lshlrev_b64 v[14:15], 9, v[14:15]
	v_cvt_pk_bf16_f32 v11, v19, v21
	v_cvt_pk_bf16_f32 v12, v23, v25
	v_cvt_pk_bf16_f32 v13, v27, v29
	v_lshl_add_u64 v[14:15], v[4:5], 0, v[14:15]
	global_store_dwordx4 v[14:15], v[10:13], off
	ds_read2_b32 v[14:15], v7 offset0:32 offset1:48
	ds_read2_b32 v[16:17], v7 offset0:97 offset1:113
	ds_read2_b32 v[18:19], v7 offset0:162 offset1:178
	ds_read2_b32 v[20:21], v7 offset0:227 offset1:243
	ds_read2_b32 v[22:23], v9 offset0:36 offset1:52
	ds_read2_b32 v[24:25], v9 offset0:101 offset1:117
	ds_read2_b32 v[26:27], v9 offset0:166 offset1:182
	ds_read2_b32 v[28:29], v9 offset0:231 offset1:247
	v_lshlrev_b64 v[32:33], 9, v[32:33]
	s_waitcnt lgkmcnt(6)
	v_cvt_pk_bf16_f32 v10, v14, v16
	s_waitcnt lgkmcnt(4)
	v_cvt_pk_bf16_f32 v11, v18, v20
	s_waitcnt lgkmcnt(2)
	v_cvt_pk_bf16_f32 v12, v22, v24
	s_waitcnt lgkmcnt(0)
	v_cvt_pk_bf16_f32 v13, v26, v28
	v_lshl_add_u64 v[32:33], v[4:5], 0, v[32:33]
	v_add_u32_e32 v14, 48, v30
	global_store_dwordx4 v[32:33], v[10:13], off
	s_cmpk_lt_i32 s6, 0x80
	s_nop 0
	v_cvt_pk_bf16_f32 v10, v15, v17
	v_ashrrev_i32_e32 v15, 31, v14
	v_lshlrev_b64 v[14:15], 9, v[14:15]
	v_cvt_pk_bf16_f32 v11, v19, v21
	v_cvt_pk_bf16_f32 v12, v23, v25
	v_cvt_pk_bf16_f32 v13, v27, v29
	v_lshl_add_u64 v[4:5], v[4:5], 0, v[14:15]
	global_store_dwordx4 v[4:5], v[10:13], off
	s_waitcnt lgkmcnt(0)
	s_cbranch_scc1 .LBB0_392

.LBB0_869:
	s_ashr_i32 s12, s9, 31
	s_lshr_b32 s12, s12, 29
	s_add_i32 s12, s9, s12
	s_ashr_i32 s13, s12, 3
	s_lshl_b32 s14, s13, 9
	s_lshl_b32 s12, s13, 5
	s_sub_i32 s13, s7, s14
	v_add_u32_e32 v4, s13, v40
	v_ashrrev_i32_e32 v5, 31, v4
	s_ashr_i32 s13, s12, 31
	v_lshl_add_u64 v[26:27], v[4:5], 2, s[0:1]
	s_lshl_b64 s[18:19], s[12:13], 11
	v_lshl_add_u64 v[4:5], v[26:27], 0, s[18:19]
	s_or_b32 s18, s12, 1
	s_ashr_i32 s19, s18, 31
	s_lshl_b64 s[18:19], s[18:19], 11
	v_lshl_add_u64 v[6:7], v[26:27], 0, s[18:19]
	s_or_b32 s18, s12, 2
	s_ashr_i32 s19, s18, 31
	s_lshl_b64 s[18:19], s[18:19], 11
	global_load_dword v4, v[4:5], off nt
	s_andn2_b64 vcc, exec, s[10:11]
	global_load_dword v5, v[6:7], off nt
	v_lshl_add_u64 v[6:7], v[26:27], 0, s[18:19]
	s_or_b32 s18, s12, 3
	s_ashr_i32 s19, s18, 31
	s_lshl_b64 s[18:19], s[18:19], 11
	v_lshl_add_u64 v[8:9], v[26:27], 0, s[18:19]
	s_or_b32 s18, s12, 4
	s_ashr_i32 s19, s18, 31
	s_lshl_b64 s[18:19], s[18:19], 11
	global_load_dword v6, v[6:7], off nt
	s_nop 0
	global_load_dword v7, v[8:9], off nt
	v_lshl_add_u64 v[8:9], v[26:27], 0, s[18:19]
	s_or_b32 s18, s12, 5
	s_ashr_i32 s19, s18, 31
	s_lshl_b64 s[18:19], s[18:19], 11
	v_lshl_add_u64 v[10:11], v[26:27], 0, s[18:19]
	s_or_b32 s18, s12, 6
	s_ashr_i32 s19, s18, 31
	s_lshl_b64 s[18:19], s[18:19], 11
	global_load_dword v8, v[8:9], off nt
	s_nop 0
	global_load_dword v9, v[10:11], off nt
	v_lshl_add_u64 v[10:11], v[26:27], 0, s[18:19]
	s_or_b32 s18, s12, 7
	s_ashr_i32 s19, s18, 31
	s_lshl_b64 s[18:19], s[18:19], 11
	v_lshl_add_u64 v[12:13], v[26:27], 0, s[18:19]
	s_or_b32 s18, s12, 8
	s_ashr_i32 s19, s18, 31
	s_lshl_b64 s[18:19], s[18:19], 11
	global_load_dword v10, v[10:11], off nt
	s_nop 0
	global_load_dword v11, v[12:13], off nt
	v_lshl_add_u64 v[12:13], v[26:27], 0, s[18:19]
	s_or_b32 s18, s12, 9
	s_ashr_i32 s19, s18, 31
	s_lshl_b64 s[18:19], s[18:19], 11
	v_lshl_add_u64 v[14:15], v[26:27], 0, s[18:19]
	s_or_b32 s18, s12, 10
	s_ashr_i32 s19, s18, 31
	s_lshl_b64 s[18:19], s[18:19], 11
	global_load_dword v12, v[12:13], off nt
	s_nop 0
	global_load_dword v13, v[14:15], off nt
	v_lshl_add_u64 v[14:15], v[26:27], 0, s[18:19]
	s_or_b32 s18, s12, 11
	s_ashr_i32 s19, s18, 31
	s_lshl_b64 s[18:19], s[18:19], 11
	v_lshl_add_u64 v[16:17], v[26:27], 0, s[18:19]
	s_or_b32 s18, s12, 12
	s_ashr_i32 s19, s18, 31
	s_lshl_b64 s[18:19], s[18:19], 11
	global_load_dword v14, v[14:15], off nt
	s_nop 0
	global_load_dword v15, v[16:17], off nt
	v_lshl_add_u64 v[16:17], v[26:27], 0, s[18:19]
	s_or_b32 s18, s12, 13
	s_ashr_i32 s19, s18, 31
	s_lshl_b64 s[18:19], s[18:19], 11
	v_lshl_add_u64 v[18:19], v[26:27], 0, s[18:19]
	s_or_b32 s18, s12, 14
	s_ashr_i32 s19, s18, 31
	s_lshl_b64 s[18:19], s[18:19], 11
	global_load_dword v16, v[16:17], off nt
	s_nop 0
	global_load_dword v17, v[18:19], off nt
	v_lshl_add_u64 v[18:19], v[26:27], 0, s[18:19]
	s_or_b32 s18, s12, 15
	s_ashr_i32 s19, s18, 31
	s_lshl_b64 s[18:19], s[18:19], 11
	v_lshl_add_u64 v[20:21], v[26:27], 0, s[18:19]
	s_or_b32 s18, s12, 16
	s_ashr_i32 s19, s18, 31
	s_lshl_b64 s[18:19], s[18:19], 11
	global_load_dword v18, v[18:19], off nt
	s_nop 0
	global_load_dword v19, v[20:21], off nt
	v_lshl_add_u64 v[20:21], v[26:27], 0, s[18:19]
	s_or_b32 s18, s12, 17
	s_ashr_i32 s19, s18, 31
	s_lshl_b64 s[18:19], s[18:19], 11
	v_lshl_add_u64 v[22:23], v[26:27], 0, s[18:19]
	s_or_b32 s18, s12, 18
	s_ashr_i32 s19, s18, 31
	s_lshl_b64 s[18:19], s[18:19], 11
	global_load_dword v20, v[20:21], off nt
	s_nop 0
	global_load_dword v21, v[22:23], off nt
	v_lshl_add_u64 v[22:23], v[26:27], 0, s[18:19]
	s_or_b32 s18, s12, 19
	s_ashr_i32 s19, s18, 31
	s_lshl_b64 s[18:19], s[18:19], 11
	v_lshl_add_u64 v[24:25], v[26:27], 0, s[18:19]
	s_or_b32 s18, s12, 20
	s_ashr_i32 s19, s18, 31
	s_lshl_b64 s[18:19], s[18:19], 11
	global_load_dword v22, v[22:23], off nt
	s_nop 0
	global_load_dword v23, v[24:25], off nt
	v_lshl_add_u64 v[24:25], v[26:27], 0, s[18:19]
	s_or_b32 s18, s12, 21
	s_ashr_i32 s19, s18, 31
	s_lshl_b64 s[18:19], s[18:19], 11
	v_lshl_add_u64 v[28:29], v[26:27], 0, s[18:19]
	s_or_b32 s18, s12, 22
	s_ashr_i32 s19, s18, 31
	s_lshl_b64 s[18:19], s[18:19], 11
	global_load_dword v24, v[24:25], off nt
	s_nop 0
	global_load_dword v25, v[28:29], off nt
	v_lshl_add_u64 v[28:29], v[26:27], 0, s[18:19]
	s_or_b32 s18, s12, 23
	s_ashr_i32 s19, s18, 31
	s_lshl_b64 s[18:19], s[18:19], 11
	v_lshl_add_u64 v[30:31], v[26:27], 0, s[18:19]
	s_or_b32 s18, s12, 24
	s_ashr_i32 s19, s18, 31
	s_lshl_b64 s[18:19], s[18:19], 11
	global_load_dword v28, v[28:29], off nt
	s_nop 0
	global_load_dword v29, v[30:31], off nt
	v_lshl_add_u64 v[30:31], v[26:27], 0, s[18:19]
	s_or_b32 s18, s12, 25
	s_ashr_i32 s19, s18, 31
	s_lshl_b64 s[18:19], s[18:19], 11
	v_lshl_add_u64 v[32:33], v[26:27], 0, s[18:19]
	s_or_b32 s18, s12, 26
	s_ashr_i32 s19, s18, 31
	s_lshl_b64 s[18:19], s[18:19], 11
	global_load_dword v30, v[30:31], off nt
	s_nop 0
	global_load_dword v31, v[32:33], off nt
	v_lshl_add_u64 v[32:33], v[26:27], 0, s[18:19]
	s_or_b32 s18, s12, 27
	s_ashr_i32 s19, s18, 31
	s_lshl_b64 s[18:19], s[18:19], 11
	v_lshl_add_u64 v[34:35], v[26:27], 0, s[18:19]
	s_or_b32 s18, s12, 28
	s_ashr_i32 s19, s18, 31
	s_lshl_b64 s[18:19], s[18:19], 11
	global_load_dword v32, v[32:33], off nt
	s_nop 0
	global_load_dword v33, v[34:35], off nt
	v_lshl_add_u64 v[34:35], v[26:27], 0, s[18:19]
	s_or_b32 s18, s12, 29
	s_ashr_i32 s19, s18, 31
	s_lshl_b64 s[18:19], s[18:19], 11
	v_lshl_add_u64 v[36:37], v[26:27], 0, s[18:19]
	s_or_b32 s18, s12, 30
	s_ashr_i32 s19, s18, 31
	s_lshl_b64 s[18:19], s[18:19], 11
	global_load_dword v34, v[34:35], off nt
	s_nop 0
	global_load_dword v35, v[36:37], off nt
	v_lshl_add_u64 v[36:37], v[26:27], 0, s[18:19]
	s_or_b32 s18, s12, 31
	s_ashr_i32 s19, s18, 31
	s_lshl_b64 s[18:19], s[18:19], 11
	v_lshl_add_u64 v[26:27], v[26:27], 0, s[18:19]
	global_load_dword v36, v[36:37], off nt
	s_nop 0
	global_load_dword v37, v[26:27], off nt
	s_cbranch_vccnz .LBB0_868
	s_lshl_b64 s[18:19], s[12:13], 2
	s_add_u32 s18, s5, s18
	s_addc_u32 s19, s6, s19
	global_load_dwordx4 v[42:45], v0, s[18:19]
	global_load_dwordx4 v[46:49], v0, s[18:19] offset:16
	global_load_dwordx4 v[50:53], v0, s[18:19] offset:32
	global_load_dwordx4 v[54:57], v0, s[18:19] offset:48
	global_load_dwordx4 v[58:61], v0, s[18:19] offset:64
	global_load_dwordx4 v[62:65], v0, s[18:19] offset:80
	global_load_dwordx4 v[66:69], v0, s[18:19] offset:96
	global_load_dwordx4 v[70:73], v0, s[18:19] offset:112
	s_waitcnt vmcnt(7)
	v_pk_mul_f32 v[4:5], v[4:5], v[42:43]
	v_pk_mul_f32 v[6:7], v[6:7], v[44:45]
	s_waitcnt vmcnt(6)
	v_pk_mul_f32 v[8:9], v[8:9], v[46:47]
	v_pk_mul_f32 v[10:11], v[10:11], v[48:49]
	s_waitcnt vmcnt(5)
	v_pk_mul_f32 v[12:13], v[12:13], v[50:51]
	v_pk_mul_f32 v[14:15], v[14:15], v[52:53]
	s_waitcnt vmcnt(4)
	v_pk_mul_f32 v[16:17], v[16:17], v[54:55]
	v_pk_mul_f32 v[18:19], v[18:19], v[56:57]
	s_waitcnt vmcnt(3)
	v_pk_mul_f32 v[20:21], v[20:21], v[58:59]
	v_pk_mul_f32 v[22:23], v[22:23], v[60:61]
	s_waitcnt vmcnt(2)
	v_pk_mul_f32 v[24:25], v[24:25], v[62:63]
	v_pk_mul_f32 v[28:29], v[28:29], v[64:65]
	s_waitcnt vmcnt(1)
	v_pk_mul_f32 v[30:31], v[30:31], v[66:67]
	v_pk_mul_f32 v[32:33], v[32:33], v[68:69]
	s_waitcnt vmcnt(0)
	v_pk_mul_f32 v[34:35], v[34:35], v[70:71]
	v_pk_mul_f32 v[36:37], v[36:37], v[72:73]
	s_branch .LBB0_868

.LBB0_875:
	s_ashr_i32 s8, s7, 31
	s_lshr_b32 s8, s8, 30
	s_add_i32 s8, s7, s8
	s_ashr_i32 s8, s8, 2
	s_lshl_b32 s24, s8, 5
	s_lshl_b32 s8, s8, 8
	s_sub_i32 s9, s5, s8
	v_add_u32_e32 v4, s9, v38
	v_ashrrev_i32_e32 v5, 31, v4
	v_lshl_add_u64 v[40:41], v[4:5], 2, s[10:11]
	s_or_b32 s9, s24, 1
	v_mad_i64_i32 v[4:5], s[14:15], s24, v249, v[40:41]
	v_mad_i64_i32 v[6:7], s[14:15], s9, v249, v[40:41]
	s_or_b32 s9, s24, 2
	global_load_dword v4, v[4:5], off nt
	s_andn2_b64 vcc, exec, s[12:13]
	global_load_dword v5, v[6:7], off nt
	v_mad_i64_i32 v[6:7], s[14:15], s9, v249, v[40:41]
	s_or_b32 s9, s24, 3
	v_mad_i64_i32 v[8:9], s[14:15], s9, v249, v[40:41]
	s_or_b32 s9, s24, 4
	global_load_dword v6, v[6:7], off nt
	s_ashr_i32 s25, s24, 31
	global_load_dword v7, v[8:9], off nt
	v_mad_i64_i32 v[8:9], s[14:15], s9, v249, v[40:41]
	s_or_b32 s9, s24, 5
	v_mad_i64_i32 v[10:11], s[14:15], s9, v249, v[40:41]
	s_or_b32 s9, s24, 6
	global_load_dword v8, v[8:9], off nt
	s_nop 0
	global_load_dword v9, v[10:11], off nt
	v_mad_i64_i32 v[10:11], s[14:15], s9, v249, v[40:41]
	s_or_b32 s9, s24, 7
	v_mad_i64_i32 v[12:13], s[14:15], s9, v249, v[40:41]
	s_or_b32 s9, s24, 8
	global_load_dword v10, v[10:11], off nt
	s_nop 0
	global_load_dword v11, v[12:13], off nt
	v_mad_i64_i32 v[12:13], s[14:15], s9, v249, v[40:41]
	s_or_b32 s9, s24, 9
	v_mad_i64_i32 v[14:15], s[14:15], s9, v249, v[40:41]
	s_or_b32 s9, s24, 10
	global_load_dword v12, v[12:13], off nt
	s_nop 0
	global_load_dword v13, v[14:15], off nt
	v_mad_i64_i32 v[14:15], s[14:15], s9, v249, v[40:41]
	s_or_b32 s9, s24, 11
	v_mad_i64_i32 v[16:17], s[14:15], s9, v249, v[40:41]
	s_or_b32 s9, s24, 12
	global_load_dword v14, v[14:15], off nt
	s_nop 0
	global_load_dword v15, v[16:17], off nt
	v_mad_i64_i32 v[16:17], s[14:15], s9, v249, v[40:41]
	s_or_b32 s9, s24, 13
	v_mad_i64_i32 v[18:19], s[14:15], s9, v249, v[40:41]
	s_or_b32 s9, s24, 14
	global_load_dword v16, v[16:17], off nt
	s_nop 0
	global_load_dword v17, v[18:19], off nt
	v_mad_i64_i32 v[18:19], s[14:15], s9, v249, v[40:41]
	s_or_b32 s9, s24, 15
	v_mad_i64_i32 v[20:21], s[14:15], s9, v249, v[40:41]
	s_or_b32 s9, s24, 16
	global_load_dword v18, v[18:19], off nt
	s_nop 0
	global_load_dword v19, v[20:21], off nt
	v_mad_i64_i32 v[20:21], s[14:15], s9, v249, v[40:41]
	s_or_b32 s9, s24, 17
	v_mad_i64_i32 v[22:23], s[14:15], s9, v249, v[40:41]
	s_or_b32 s9, s24, 18
	global_load_dword v20, v[20:21], off nt
	s_nop 0
	global_load_dword v21, v[22:23], off nt
	v_mad_i64_i32 v[22:23], s[14:15], s9, v249, v[40:41]
	s_or_b32 s9, s24, 19
	v_mad_i64_i32 v[24:25], s[14:15], s9, v249, v[40:41]
	s_or_b32 s9, s24, 20
	global_load_dword v22, v[22:23], off nt
	s_nop 0
	global_load_dword v23, v[24:25], off nt
	v_mad_i64_i32 v[24:25], s[14:15], s9, v249, v[40:41]
	s_or_b32 s9, s24, 21
	v_mad_i64_i32 v[26:27], s[14:15], s9, v249, v[40:41]
	s_or_b32 s9, s24, 22
	global_load_dword v24, v[24:25], off nt
	s_nop 0
	global_load_dword v25, v[26:27], off nt
	v_mad_i64_i32 v[26:27], s[14:15], s9, v249, v[40:41]
	s_or_b32 s9, s24, 23
	v_mad_i64_i32 v[28:29], s[14:15], s9, v249, v[40:41]
	s_or_b32 s9, s24, 24
	global_load_dword v26, v[26:27], off nt
	s_nop 0
	global_load_dword v27, v[28:29], off nt
	v_mad_i64_i32 v[28:29], s[14:15], s9, v249, v[40:41]
	s_or_b32 s9, s24, 25
	v_mad_i64_i32 v[30:31], s[14:15], s9, v249, v[40:41]
	s_or_b32 s9, s24, 26
	global_load_dword v28, v[28:29], off nt
	s_nop 0
	global_load_dword v29, v[30:31], off nt
	v_mad_i64_i32 v[30:31], s[14:15], s9, v249, v[40:41]
	s_or_b32 s9, s24, 27
	v_mad_i64_i32 v[32:33], s[14:15], s9, v249, v[40:41]
	s_or_b32 s9, s24, 28
	global_load_dword v30, v[30:31], off nt
	s_nop 0
	global_load_dword v31, v[32:33], off nt
	v_mad_i64_i32 v[32:33], s[14:15], s9, v249, v[40:41]
	s_or_b32 s9, s24, 29
	v_mad_i64_i32 v[34:35], s[14:15], s9, v249, v[40:41]
	s_or_b32 s9, s24, 30
	global_load_dword v32, v[32:33], off nt
	s_nop 0
	global_load_dword v33, v[34:35], off nt
	v_mad_i64_i32 v[34:35], s[14:15], s9, v249, v[40:41]
	s_or_b32 s9, s24, 31
	v_mad_i64_i32 v[40:41], s[14:15], s9, v249, v[40:41]
	global_load_dword v34, v[34:35], off nt
	s_nop 0
	global_load_dword v35, v[40:41], off nt
	s_cbranch_vccnz .LBB0_874
	s_lshl_b64 s[14:15], s[24:25], 2
	s_add_u32 s14, s0, s14
	s_addc_u32 s15, s1, s15
	global_load_dwordx4 v[40:43], v0, s[14:15]
	global_load_dwordx4 v[44:47], v0, s[14:15] offset:16
	global_load_dwordx4 v[48:51], v0, s[14:15] offset:32
	global_load_dwordx4 v[52:55], v0, s[14:15] offset:48
	global_load_dwordx4 v[56:59], v0, s[14:15] offset:64
	global_load_dwordx4 v[60:63], v0, s[14:15] offset:80
	global_load_dwordx4 v[64:67], v0, s[14:15] offset:96
	global_load_dwordx4 v[68:71], v0, s[14:15] offset:112
	s_waitcnt vmcnt(7)
	v_pk_mul_f32 v[4:5], v[4:5], v[40:41]
	v_pk_mul_f32 v[6:7], v[6:7], v[42:43]
	s_waitcnt vmcnt(6)
	v_pk_mul_f32 v[8:9], v[8:9], v[44:45]
	v_pk_mul_f32 v[10:11], v[10:11], v[46:47]
	s_waitcnt vmcnt(5)
	v_pk_mul_f32 v[12:13], v[12:13], v[48:49]
	v_pk_mul_f32 v[14:15], v[14:15], v[50:51]
	s_waitcnt vmcnt(4)
	v_pk_mul_f32 v[16:17], v[16:17], v[52:53]
	v_pk_mul_f32 v[18:19], v[18:19], v[54:55]
	s_waitcnt vmcnt(3)
	v_pk_mul_f32 v[20:21], v[20:21], v[56:57]
	v_pk_mul_f32 v[22:23], v[22:23], v[58:59]
	s_waitcnt vmcnt(2)
	v_pk_mul_f32 v[24:25], v[24:25], v[60:61]
	v_pk_mul_f32 v[26:27], v[26:27], v[62:63]
	s_waitcnt vmcnt(1)
	v_pk_mul_f32 v[28:29], v[28:29], v[64:65]
	v_pk_mul_f32 v[30:31], v[30:31], v[66:67]
	s_waitcnt vmcnt(0)
	v_pk_mul_f32 v[32:33], v[32:33], v[68:69]
	v_pk_mul_f32 v[34:35], v[34:35], v[70:71]
	s_branch .LBB0_874

.LBB0_880:
	v_add_u32_e32 v46, s12, v1
	s_movk_i32 s8, 0x500
	v_mad_i64_i32 v[14:15], s[6:7], v46, s8, v[2:3]
	global_load_dword v15, v[14:15], off offset:1024 nt
	v_add_u32_e32 v14, 2, v46
	v_mad_i64_i32 v[16:17], s[6:7], v14, s8, v[2:3]
	global_load_dword v14, v[16:17], off offset:1024 nt
	v_add_u32_e32 v16, 4, v46
	v_mad_i64_i32 v[16:17], s[6:7], v16, s8, v[2:3]
	global_load_dword v17, v[16:17], off offset:1024 nt
	v_add_u32_e32 v16, 6, v46
	v_mad_i64_i32 v[18:19], s[6:7], v16, s8, v[2:3]
	global_load_dword v16, v[18:19], off offset:1024 nt
	v_add_u32_e32 v18, 8, v46
	v_mad_i64_i32 v[18:19], s[6:7], v18, s8, v[2:3]
	global_load_dword v19, v[18:19], off offset:1024 nt
	v_add_u32_e32 v18, 10, v46
	v_mad_i64_i32 v[20:21], s[6:7], v18, s8, v[2:3]
	global_load_dword v18, v[20:21], off offset:1024 nt
	v_add_u32_e32 v20, 12, v46
	v_mad_i64_i32 v[20:21], s[6:7], v20, s8, v[2:3]
	global_load_dword v21, v[20:21], off offset:1024 nt
	v_add_u32_e32 v20, 14, v46
	v_mad_i64_i32 v[22:23], s[6:7], v20, s8, v[2:3]
	global_load_dword v20, v[22:23], off offset:1024 nt
	v_add_u32_e32 v22, 16, v46
	v_mad_i64_i32 v[22:23], s[6:7], v22, s8, v[2:3]
	global_load_dword v23, v[22:23], off offset:1024 nt
	v_add_u32_e32 v22, 18, v46
	v_mad_i64_i32 v[24:25], s[6:7], v22, s8, v[2:3]
	global_load_dword v22, v[24:25], off offset:1024 nt
	v_add_u32_e32 v24, 20, v46
	v_mad_i64_i32 v[24:25], s[6:7], v24, s8, v[2:3]
	global_load_dword v25, v[24:25], off offset:1024 nt
	v_add_u32_e32 v24, 22, v46
	v_mad_i64_i32 v[26:27], s[6:7], v24, s8, v[2:3]
	global_load_dword v24, v[26:27], off offset:1024 nt
	v_add_u32_e32 v26, 24, v46
	v_mad_i64_i32 v[26:27], s[6:7], v26, s8, v[2:3]
	global_load_dword v27, v[26:27], off offset:1024 nt
	v_add_u32_e32 v26, 26, v46
	v_mad_i64_i32 v[28:29], s[6:7], v26, s8, v[2:3]
	global_load_dword v26, v[28:29], off offset:1024 nt
	v_add_u32_e32 v28, 28, v46
	v_mad_i64_i32 v[28:29], s[6:7], v28, s8, v[2:3]
	global_load_dword v29, v[28:29], off offset:1024 nt
	v_add_u32_e32 v28, 30, v46
	v_mad_i64_i32 v[30:31], s[6:7], v28, s8, v[2:3]
	global_load_dword v28, v[30:31], off offset:1024 nt
	v_add_u32_e32 v30, 32, v46
	v_mad_i64_i32 v[30:31], s[6:7], v30, s8, v[2:3]
	global_load_dword v31, v[30:31], off offset:1024 nt
	v_add_u32_e32 v30, 34, v46
	v_mad_i64_i32 v[32:33], s[6:7], v30, s8, v[2:3]
	global_load_dword v30, v[32:33], off offset:1024 nt
	v_add_u32_e32 v32, 36, v46
	v_mad_i64_i32 v[32:33], s[6:7], v32, s8, v[2:3]
	global_load_dword v33, v[32:33], off offset:1024 nt
	v_add_u32_e32 v32, 38, v46
	v_mad_i64_i32 v[34:35], s[6:7], v32, s8, v[2:3]
	global_load_dword v32, v[34:35], off offset:1024 nt
	v_add_u32_e32 v34, 40, v46
	v_mad_i64_i32 v[34:35], s[6:7], v34, s8, v[2:3]
	global_load_dword v35, v[34:35], off offset:1024 nt
	v_add_u32_e32 v34, 42, v46
	v_mad_i64_i32 v[36:37], s[6:7], v34, s8, v[2:3]
	global_load_dword v34, v[36:37], off offset:1024 nt
	v_add_u32_e32 v36, 44, v46
	v_mad_i64_i32 v[36:37], s[6:7], v36, s8, v[2:3]
	global_load_dword v37, v[36:37], off offset:1024 nt
	v_add_u32_e32 v36, 46, v46
	v_mad_i64_i32 v[38:39], s[6:7], v36, s8, v[2:3]
	global_load_dword v36, v[38:39], off offset:1024 nt
	v_add_u32_e32 v38, 48, v46
	v_mad_i64_i32 v[38:39], s[6:7], v38, s8, v[2:3]
	global_load_dword v39, v[38:39], off offset:1024 nt
	v_add_u32_e32 v38, 50, v46
	v_mad_i64_i32 v[40:41], s[6:7], v38, s8, v[2:3]
	global_load_dword v38, v[40:41], off offset:1024 nt
	v_add_u32_e32 v40, 52, v46
	v_mad_i64_i32 v[40:41], s[6:7], v40, s8, v[2:3]
	global_load_dword v41, v[40:41], off offset:1024 nt
	v_add_u32_e32 v40, 54, v46
	v_mad_i64_i32 v[42:43], s[6:7], v40, s8, v[2:3]
	global_load_dword v40, v[42:43], off offset:1024 nt
	v_add_u32_e32 v42, 56, v46
	v_mad_i64_i32 v[42:43], s[6:7], v42, s8, v[2:3]
	global_load_dword v43, v[42:43], off offset:1024 nt
	v_add_u32_e32 v42, 58, v46
	v_mad_i64_i32 v[44:45], s[6:7], v42, s8, v[2:3]
	global_load_dword v42, v[44:45], off offset:1024 nt
	v_add_u32_e32 v44, 60, v46
	v_mad_i64_i32 v[44:45], s[6:7], v44, s8, v[2:3]
	global_load_dword v45, v[44:45], off offset:1024 nt
	v_add_u32_e32 v44, 62, v46
	v_mad_i64_i32 v[50:51], s[6:7], v44, s8, v[2:3]
	global_load_dword v44, v[50:51], off offset:1024 nt
	s_andn2_b64 vcc, exec, s[10:11]
	s_cbranch_vccnz .LBB0_879
	v_ashrrev_i32_e32 v47, 31, v46
	v_lshl_add_u64 v[46:47], v[46:47], 2, s[0:1]
	global_load_dword v51, v[46:47], off nt
	global_load_dword v50, v[46:47], off offset:8 nt
	s_waitcnt vmcnt(0)
	v_pk_mul_f32 v[14:15], v[14:15], v[50:51]
	global_load_dword v51, v[46:47], off offset:16 nt
	global_load_dword v50, v[46:47], off offset:24 nt
	s_waitcnt vmcnt(0)
	v_pk_mul_f32 v[16:17], v[16:17], v[50:51]
	global_load_dword v51, v[46:47], off offset:32 nt
	global_load_dword v50, v[46:47], off offset:40 nt
	s_waitcnt vmcnt(0)
	v_pk_mul_f32 v[18:19], v[18:19], v[50:51]
	global_load_dword v51, v[46:47], off offset:48 nt
	global_load_dword v50, v[46:47], off offset:56 nt
	s_waitcnt vmcnt(0)
	v_pk_mul_f32 v[20:21], v[20:21], v[50:51]
	global_load_dword v51, v[46:47], off offset:64 nt
	global_load_dword v50, v[46:47], off offset:72 nt
	s_waitcnt vmcnt(0)
	v_pk_mul_f32 v[22:23], v[22:23], v[50:51]
	global_load_dword v51, v[46:47], off offset:80 nt
	global_load_dword v50, v[46:47], off offset:88 nt
	s_waitcnt vmcnt(0)
	v_pk_mul_f32 v[24:25], v[24:25], v[50:51]
	global_load_dword v51, v[46:47], off offset:96 nt
	global_load_dword v50, v[46:47], off offset:104 nt
	s_waitcnt vmcnt(0)
	v_pk_mul_f32 v[26:27], v[26:27], v[50:51]
	global_load_dword v51, v[46:47], off offset:112 nt
	global_load_dword v50, v[46:47], off offset:120 nt
	s_waitcnt vmcnt(0)
	v_pk_mul_f32 v[28:29], v[28:29], v[50:51]
	global_load_dword v51, v[46:47], off offset:128 nt
	global_load_dword v50, v[46:47], off offset:136 nt
	s_waitcnt vmcnt(0)
	v_pk_mul_f32 v[30:31], v[30:31], v[50:51]
	global_load_dword v51, v[46:47], off offset:144 nt
	global_load_dword v50, v[46:47], off offset:152 nt
	s_waitcnt vmcnt(0)
	v_pk_mul_f32 v[32:33], v[32:33], v[50:51]
	global_load_dword v51, v[46:47], off offset:160 nt
	global_load_dword v50, v[46:47], off offset:168 nt
	s_waitcnt vmcnt(0)
	v_pk_mul_f32 v[34:35], v[34:35], v[50:51]
	global_load_dword v51, v[46:47], off offset:176 nt
	global_load_dword v50, v[46:47], off offset:184 nt
	s_waitcnt vmcnt(0)
	v_pk_mul_f32 v[36:37], v[36:37], v[50:51]
	global_load_dword v51, v[46:47], off offset:192 nt
	global_load_dword v50, v[46:47], off offset:200 nt
	s_waitcnt vmcnt(0)
	v_pk_mul_f32 v[38:39], v[38:39], v[50:51]
	global_load_dword v51, v[46:47], off offset:208 nt
	global_load_dword v50, v[46:47], off offset:216 nt
	s_waitcnt vmcnt(0)
	v_pk_mul_f32 v[40:41], v[40:41], v[50:51]
	global_load_dword v51, v[46:47], off offset:224 nt
	global_load_dword v50, v[46:47], off offset:232 nt
	s_waitcnt vmcnt(0)
	v_pk_mul_f32 v[42:43], v[42:43], v[50:51]
	global_load_dword v51, v[46:47], off offset:240 nt
	global_load_dword v50, v[46:47], off offset:248 nt
	s_waitcnt vmcnt(0)
	v_pk_mul_f32 v[44:45], v[44:45], v[50:51]
	s_branch .LBB0_879

.LBB0_885:
	v_add_u32_e32 v46, s12, v1
	s_movk_i32 s8, 0x500
	v_mad_i64_i32 v[14:15], s[6:7], v46, s8, v[2:3]
	global_load_dword v15, v[14:15], off offset:1152 nt
	v_add_u32_e32 v14, 2, v46
	v_mad_i64_i32 v[16:17], s[6:7], v14, s8, v[2:3]
	global_load_dword v14, v[16:17], off offset:1152 nt
	v_add_u32_e32 v16, 4, v46
	v_mad_i64_i32 v[16:17], s[6:7], v16, s8, v[2:3]
	global_load_dword v17, v[16:17], off offset:1152 nt
	v_add_u32_e32 v16, 6, v46
	v_mad_i64_i32 v[18:19], s[6:7], v16, s8, v[2:3]
	global_load_dword v16, v[18:19], off offset:1152 nt
	v_add_u32_e32 v18, 8, v46
	v_mad_i64_i32 v[18:19], s[6:7], v18, s8, v[2:3]
	global_load_dword v19, v[18:19], off offset:1152 nt
	v_add_u32_e32 v18, 10, v46
	v_mad_i64_i32 v[20:21], s[6:7], v18, s8, v[2:3]
	global_load_dword v18, v[20:21], off offset:1152 nt
	v_add_u32_e32 v20, 12, v46
	v_mad_i64_i32 v[20:21], s[6:7], v20, s8, v[2:3]
	global_load_dword v21, v[20:21], off offset:1152 nt
	v_add_u32_e32 v20, 14, v46
	v_mad_i64_i32 v[22:23], s[6:7], v20, s8, v[2:3]
	global_load_dword v20, v[22:23], off offset:1152 nt
	v_add_u32_e32 v22, 16, v46
	v_mad_i64_i32 v[22:23], s[6:7], v22, s8, v[2:3]
	global_load_dword v23, v[22:23], off offset:1152 nt
	v_add_u32_e32 v22, 18, v46
	v_mad_i64_i32 v[24:25], s[6:7], v22, s8, v[2:3]
	global_load_dword v22, v[24:25], off offset:1152 nt
	v_add_u32_e32 v24, 20, v46
	v_mad_i64_i32 v[24:25], s[6:7], v24, s8, v[2:3]
	global_load_dword v25, v[24:25], off offset:1152 nt
	v_add_u32_e32 v24, 22, v46
	v_mad_i64_i32 v[26:27], s[6:7], v24, s8, v[2:3]
	global_load_dword v24, v[26:27], off offset:1152 nt
	v_add_u32_e32 v26, 24, v46
	v_mad_i64_i32 v[26:27], s[6:7], v26, s8, v[2:3]
	global_load_dword v27, v[26:27], off offset:1152 nt
	v_add_u32_e32 v26, 26, v46
	v_mad_i64_i32 v[28:29], s[6:7], v26, s8, v[2:3]
	global_load_dword v26, v[28:29], off offset:1152 nt
	v_add_u32_e32 v28, 28, v46
	v_mad_i64_i32 v[28:29], s[6:7], v28, s8, v[2:3]
	global_load_dword v29, v[28:29], off offset:1152 nt
	v_add_u32_e32 v28, 30, v46
	v_mad_i64_i32 v[30:31], s[6:7], v28, s8, v[2:3]
	global_load_dword v28, v[30:31], off offset:1152 nt
	v_add_u32_e32 v30, 32, v46
	v_mad_i64_i32 v[30:31], s[6:7], v30, s8, v[2:3]
	global_load_dword v31, v[30:31], off offset:1152 nt
	v_add_u32_e32 v30, 34, v46
	v_mad_i64_i32 v[32:33], s[6:7], v30, s8, v[2:3]
	global_load_dword v30, v[32:33], off offset:1152 nt
	v_add_u32_e32 v32, 36, v46
	v_mad_i64_i32 v[32:33], s[6:7], v32, s8, v[2:3]
	global_load_dword v33, v[32:33], off offset:1152 nt
	v_add_u32_e32 v32, 38, v46
	v_mad_i64_i32 v[34:35], s[6:7], v32, s8, v[2:3]
	global_load_dword v32, v[34:35], off offset:1152 nt
	v_add_u32_e32 v34, 40, v46
	v_mad_i64_i32 v[34:35], s[6:7], v34, s8, v[2:3]
	global_load_dword v35, v[34:35], off offset:1152 nt
	v_add_u32_e32 v34, 42, v46
	v_mad_i64_i32 v[36:37], s[6:7], v34, s8, v[2:3]
	global_load_dword v34, v[36:37], off offset:1152 nt
	v_add_u32_e32 v36, 44, v46
	v_mad_i64_i32 v[36:37], s[6:7], v36, s8, v[2:3]
	global_load_dword v37, v[36:37], off offset:1152 nt
	v_add_u32_e32 v36, 46, v46
	v_mad_i64_i32 v[38:39], s[6:7], v36, s8, v[2:3]
	global_load_dword v36, v[38:39], off offset:1152 nt
	v_add_u32_e32 v38, 48, v46
	v_mad_i64_i32 v[38:39], s[6:7], v38, s8, v[2:3]
	global_load_dword v39, v[38:39], off offset:1152 nt
	v_add_u32_e32 v38, 50, v46
	v_mad_i64_i32 v[40:41], s[6:7], v38, s8, v[2:3]
	global_load_dword v38, v[40:41], off offset:1152 nt
	v_add_u32_e32 v40, 52, v46
	v_mad_i64_i32 v[40:41], s[6:7], v40, s8, v[2:3]
	global_load_dword v41, v[40:41], off offset:1152 nt
	v_add_u32_e32 v40, 54, v46
	v_mad_i64_i32 v[42:43], s[6:7], v40, s8, v[2:3]
	global_load_dword v40, v[42:43], off offset:1152 nt
	v_add_u32_e32 v42, 56, v46
	v_mad_i64_i32 v[42:43], s[6:7], v42, s8, v[2:3]
	global_load_dword v43, v[42:43], off offset:1152 nt
	v_add_u32_e32 v42, 58, v46
	v_mad_i64_i32 v[44:45], s[6:7], v42, s8, v[2:3]
	global_load_dword v42, v[44:45], off offset:1152 nt
	v_add_u32_e32 v44, 60, v46
	v_mad_i64_i32 v[44:45], s[6:7], v44, s8, v[2:3]
	global_load_dword v45, v[44:45], off offset:1152 nt
	v_add_u32_e32 v44, 62, v46
	v_mad_i64_i32 v[50:51], s[6:7], v44, s8, v[2:3]
	global_load_dword v44, v[50:51], off offset:1152 nt
	s_andn2_b64 vcc, exec, s[10:11]
	s_cbranch_vccnz .LBB0_884
	v_ashrrev_i32_e32 v47, 31, v46
	v_lshl_add_u64 v[46:47], v[46:47], 2, s[0:1]
	global_load_dword v51, v[46:47], off nt
	global_load_dword v50, v[46:47], off offset:8 nt
	s_waitcnt vmcnt(0)
	v_pk_mul_f32 v[14:15], v[14:15], v[50:51]
	global_load_dword v51, v[46:47], off offset:16 nt
	global_load_dword v50, v[46:47], off offset:24 nt
	s_waitcnt vmcnt(0)
	v_pk_mul_f32 v[16:17], v[16:17], v[50:51]
	global_load_dword v51, v[46:47], off offset:32 nt
	global_load_dword v50, v[46:47], off offset:40 nt
	s_waitcnt vmcnt(0)
	v_pk_mul_f32 v[18:19], v[18:19], v[50:51]
	global_load_dword v51, v[46:47], off offset:48 nt
	global_load_dword v50, v[46:47], off offset:56 nt
	s_waitcnt vmcnt(0)
	v_pk_mul_f32 v[20:21], v[20:21], v[50:51]
	global_load_dword v51, v[46:47], off offset:64 nt
	global_load_dword v50, v[46:47], off offset:72 nt
	s_waitcnt vmcnt(0)
	v_pk_mul_f32 v[22:23], v[22:23], v[50:51]
	global_load_dword v51, v[46:47], off offset:80 nt
	global_load_dword v50, v[46:47], off offset:88 nt
	s_waitcnt vmcnt(0)
	v_pk_mul_f32 v[24:25], v[24:25], v[50:51]
	global_load_dword v51, v[46:47], off offset:96 nt
	global_load_dword v50, v[46:47], off offset:104 nt
	s_waitcnt vmcnt(0)
	v_pk_mul_f32 v[26:27], v[26:27], v[50:51]
	global_load_dword v51, v[46:47], off offset:112 nt
	global_load_dword v50, v[46:47], off offset:120 nt
	s_waitcnt vmcnt(0)
	v_pk_mul_f32 v[28:29], v[28:29], v[50:51]
	global_load_dword v51, v[46:47], off offset:128 nt
	global_load_dword v50, v[46:47], off offset:136 nt
	s_waitcnt vmcnt(0)
	v_pk_mul_f32 v[30:31], v[30:31], v[50:51]
	global_load_dword v51, v[46:47], off offset:144 nt
	global_load_dword v50, v[46:47], off offset:152 nt
	s_waitcnt vmcnt(0)
	v_pk_mul_f32 v[32:33], v[32:33], v[50:51]
	global_load_dword v51, v[46:47], off offset:160 nt
	global_load_dword v50, v[46:47], off offset:168 nt
	s_waitcnt vmcnt(0)
	v_pk_mul_f32 v[34:35], v[34:35], v[50:51]
	global_load_dword v51, v[46:47], off offset:176 nt
	global_load_dword v50, v[46:47], off offset:184 nt
	s_waitcnt vmcnt(0)
	v_pk_mul_f32 v[36:37], v[36:37], v[50:51]
	global_load_dword v51, v[46:47], off offset:192 nt
	global_load_dword v50, v[46:47], off offset:200 nt
	s_waitcnt vmcnt(0)
	v_pk_mul_f32 v[38:39], v[38:39], v[50:51]
	global_load_dword v51, v[46:47], off offset:208 nt
	global_load_dword v50, v[46:47], off offset:216 nt
	s_waitcnt vmcnt(0)
	v_pk_mul_f32 v[40:41], v[40:41], v[50:51]
	global_load_dword v51, v[46:47], off offset:224 nt
	global_load_dword v50, v[46:47], off offset:232 nt
	s_waitcnt vmcnt(0)
	v_pk_mul_f32 v[42:43], v[42:43], v[50:51]
	global_load_dword v51, v[46:47], off offset:240 nt
	global_load_dword v50, v[46:47], off offset:248 nt
	s_waitcnt vmcnt(0)
	v_pk_mul_f32 v[44:45], v[44:45], v[50:51]
	s_branch .LBB0_884

.LBB0_890:
	s_ashr_i32 s8, s7, 31
	s_lshr_b32 s8, s8, 26
	s_add_i32 s8, s7, s8
	s_ashr_i32 s8, s8, 6
	s_lshl_b32 s24, s8, 5
	s_lshl_b32 s8, s8, 12
	s_sub_i32 s9, s5, s8
	v_add_u32_e32 v4, s9, v40
	v_ashrrev_i32_e32 v5, 31, v4
	s_ashr_i32 s25, s24, 31
	v_lshl_add_u64 v[26:27], v[4:5], 2, s[10:11]
	s_lshl_b64 s[14:15], s[24:25], 14
	v_lshl_add_u64 v[4:5], v[26:27], 0, s[14:15]
	s_or_b32 s14, s24, 1
	s_ashr_i32 s15, s14, 31
	s_lshl_b64 s[14:15], s[14:15], 14
	v_lshl_add_u64 v[6:7], v[26:27], 0, s[14:15]
	s_or_b32 s14, s24, 2
	s_ashr_i32 s15, s14, 31
	s_lshl_b64 s[14:15], s[14:15], 14
	global_load_dword v4, v[4:5], off nt
	s_andn2_b64 vcc, exec, s[12:13]
	global_load_dword v5, v[6:7], off nt
	v_lshl_add_u64 v[6:7], v[26:27], 0, s[14:15]
	s_or_b32 s14, s24, 3
	s_ashr_i32 s15, s14, 31
	s_lshl_b64 s[14:15], s[14:15], 14
	v_lshl_add_u64 v[8:9], v[26:27], 0, s[14:15]
	s_or_b32 s14, s24, 4
	s_ashr_i32 s15, s14, 31
	s_lshl_b64 s[14:15], s[14:15], 14
	global_load_dword v6, v[6:7], off nt
	s_nop 0
	global_load_dword v7, v[8:9], off nt
	v_lshl_add_u64 v[8:9], v[26:27], 0, s[14:15]
	s_or_b32 s14, s24, 5
	s_ashr_i32 s15, s14, 31
	s_lshl_b64 s[14:15], s[14:15], 14
	v_lshl_add_u64 v[10:11], v[26:27], 0, s[14:15]
	s_or_b32 s14, s24, 6
	s_ashr_i32 s15, s14, 31
	s_lshl_b64 s[14:15], s[14:15], 14
	global_load_dword v8, v[8:9], off nt
	s_nop 0
	global_load_dword v9, v[10:11], off nt
	v_lshl_add_u64 v[10:11], v[26:27], 0, s[14:15]
	s_or_b32 s14, s24, 7
	s_ashr_i32 s15, s14, 31
	s_lshl_b64 s[14:15], s[14:15], 14
	v_lshl_add_u64 v[12:13], v[26:27], 0, s[14:15]
	s_or_b32 s14, s24, 8
	s_ashr_i32 s15, s14, 31
	s_lshl_b64 s[14:15], s[14:15], 14
	global_load_dword v10, v[10:11], off nt
	s_nop 0
	global_load_dword v11, v[12:13], off nt
	v_lshl_add_u64 v[12:13], v[26:27], 0, s[14:15]
	s_or_b32 s14, s24, 9
	s_ashr_i32 s15, s14, 31
	s_lshl_b64 s[14:15], s[14:15], 14
	v_lshl_add_u64 v[14:15], v[26:27], 0, s[14:15]
	s_or_b32 s14, s24, 10
	s_ashr_i32 s15, s14, 31
	s_lshl_b64 s[14:15], s[14:15], 14
	global_load_dword v12, v[12:13], off nt
	s_nop 0
	global_load_dword v13, v[14:15], off nt
	v_lshl_add_u64 v[14:15], v[26:27], 0, s[14:15]
	s_or_b32 s14, s24, 11
	s_ashr_i32 s15, s14, 31
	s_lshl_b64 s[14:15], s[14:15], 14
	v_lshl_add_u64 v[16:17], v[26:27], 0, s[14:15]
	s_or_b32 s14, s24, 12
	s_ashr_i32 s15, s14, 31
	s_lshl_b64 s[14:15], s[14:15], 14
	global_load_dword v14, v[14:15], off nt
	s_nop 0
	global_load_dword v15, v[16:17], off nt
	v_lshl_add_u64 v[16:17], v[26:27], 0, s[14:15]
	s_or_b32 s14, s24, 13
	s_ashr_i32 s15, s14, 31
	s_lshl_b64 s[14:15], s[14:15], 14
	v_lshl_add_u64 v[18:19], v[26:27], 0, s[14:15]
	s_or_b32 s14, s24, 14
	s_ashr_i32 s15, s14, 31
	s_lshl_b64 s[14:15], s[14:15], 14
	global_load_dword v16, v[16:17], off nt
	s_nop 0
	global_load_dword v17, v[18:19], off nt
	v_lshl_add_u64 v[18:19], v[26:27], 0, s[14:15]
	s_or_b32 s14, s24, 15
	s_ashr_i32 s15, s14, 31
	s_lshl_b64 s[14:15], s[14:15], 14
	v_lshl_add_u64 v[20:21], v[26:27], 0, s[14:15]
	s_or_b32 s14, s24, 16
	s_ashr_i32 s15, s14, 31
	s_lshl_b64 s[14:15], s[14:15], 14
	global_load_dword v18, v[18:19], off nt
	s_nop 0
	global_load_dword v19, v[20:21], off nt
	v_lshl_add_u64 v[20:21], v[26:27], 0, s[14:15]
	s_or_b32 s14, s24, 17
	s_ashr_i32 s15, s14, 31
	s_lshl_b64 s[14:15], s[14:15], 14
	v_lshl_add_u64 v[22:23], v[26:27], 0, s[14:15]
	s_or_b32 s14, s24, 18
	s_ashr_i32 s15, s14, 31
	s_lshl_b64 s[14:15], s[14:15], 14
	global_load_dword v20, v[20:21], off nt
	s_nop 0
	global_load_dword v21, v[22:23], off nt
	v_lshl_add_u64 v[22:23], v[26:27], 0, s[14:15]
	s_or_b32 s14, s24, 19
	s_ashr_i32 s15, s14, 31
	s_lshl_b64 s[14:15], s[14:15], 14
	v_lshl_add_u64 v[24:25], v[26:27], 0, s[14:15]
	s_or_b32 s14, s24, 20
	s_ashr_i32 s15, s14, 31
	s_lshl_b64 s[14:15], s[14:15], 14
	global_load_dword v22, v[22:23], off nt
	s_nop 0
	global_load_dword v23, v[24:25], off nt
	v_lshl_add_u64 v[24:25], v[26:27], 0, s[14:15]
	s_or_b32 s14, s24, 21
	s_ashr_i32 s15, s14, 31
	s_lshl_b64 s[14:15], s[14:15], 14
	v_lshl_add_u64 v[28:29], v[26:27], 0, s[14:15]
	s_or_b32 s14, s24, 22
	s_ashr_i32 s15, s14, 31
	s_lshl_b64 s[14:15], s[14:15], 14
	global_load_dword v24, v[24:25], off nt
	s_nop 0
	global_load_dword v25, v[28:29], off nt
	v_lshl_add_u64 v[28:29], v[26:27], 0, s[14:15]
	s_or_b32 s14, s24, 23
	s_ashr_i32 s15, s14, 31
	s_lshl_b64 s[14:15], s[14:15], 14
	v_lshl_add_u64 v[30:31], v[26:27], 0, s[14:15]
	s_or_b32 s14, s24, 24
	s_ashr_i32 s15, s14, 31
	s_lshl_b64 s[14:15], s[14:15], 14
	global_load_dword v28, v[28:29], off nt
	s_nop 0
	global_load_dword v29, v[30:31], off nt
	v_lshl_add_u64 v[30:31], v[26:27], 0, s[14:15]
	s_or_b32 s14, s24, 25
	s_ashr_i32 s15, s14, 31
	s_lshl_b64 s[14:15], s[14:15], 14
	v_lshl_add_u64 v[32:33], v[26:27], 0, s[14:15]
	s_or_b32 s14, s24, 26
	s_ashr_i32 s15, s14, 31
	s_lshl_b64 s[14:15], s[14:15], 14
	global_load_dword v30, v[30:31], off nt
	s_nop 0
	global_load_dword v31, v[32:33], off nt
	v_lshl_add_u64 v[32:33], v[26:27], 0, s[14:15]
	s_or_b32 s14, s24, 27
	s_ashr_i32 s15, s14, 31
	s_lshl_b64 s[14:15], s[14:15], 14
	v_lshl_add_u64 v[34:35], v[26:27], 0, s[14:15]
	s_or_b32 s14, s24, 28
	s_ashr_i32 s15, s14, 31
	s_lshl_b64 s[14:15], s[14:15], 14
	global_load_dword v32, v[32:33], off nt
	s_nop 0
	global_load_dword v33, v[34:35], off nt
	v_lshl_add_u64 v[34:35], v[26:27], 0, s[14:15]
	s_or_b32 s14, s24, 29
	s_ashr_i32 s15, s14, 31
	s_lshl_b64 s[14:15], s[14:15], 14
	v_lshl_add_u64 v[36:37], v[26:27], 0, s[14:15]
	s_or_b32 s14, s24, 30
	s_ashr_i32 s15, s14, 31
	s_lshl_b64 s[14:15], s[14:15], 14
	global_load_dword v34, v[34:35], off nt
	s_nop 0
	global_load_dword v35, v[36:37], off nt
	v_lshl_add_u64 v[36:37], v[26:27], 0, s[14:15]
	s_or_b32 s14, s24, 31
	s_ashr_i32 s15, s14, 31
	s_lshl_b64 s[14:15], s[14:15], 14
	v_lshl_add_u64 v[26:27], v[26:27], 0, s[14:15]
	global_load_dword v36, v[36:37], off nt
	s_nop 0
	global_load_dword v37, v[26:27], off nt
	s_cbranch_vccnz .LBB0_889
	s_lshl_b64 s[14:15], s[24:25], 2
	s_add_u32 s14, s0, s14
	s_addc_u32 s15, s1, s15
	global_load_dwordx4 v[42:45], v0, s[14:15]
	global_load_dwordx4 v[46:49], v0, s[14:15] offset:16
	global_load_dwordx4 v[50:53], v0, s[14:15] offset:32
	global_load_dwordx4 v[54:57], v0, s[14:15] offset:48
	global_load_dwordx4 v[58:61], v0, s[14:15] offset:64
	global_load_dwordx4 v[62:65], v0, s[14:15] offset:80
	global_load_dwordx4 v[66:69], v0, s[14:15] offset:96
	global_load_dwordx4 v[70:73], v0, s[14:15] offset:112
	s_waitcnt vmcnt(7)
	v_pk_mul_f32 v[4:5], v[4:5], v[42:43]
	v_pk_mul_f32 v[6:7], v[6:7], v[44:45]
	s_waitcnt vmcnt(6)
	v_pk_mul_f32 v[8:9], v[8:9], v[46:47]
	v_pk_mul_f32 v[10:11], v[10:11], v[48:49]
	s_waitcnt vmcnt(5)
	v_pk_mul_f32 v[12:13], v[12:13], v[50:51]
	v_pk_mul_f32 v[14:15], v[14:15], v[52:53]
	s_waitcnt vmcnt(4)
	v_pk_mul_f32 v[16:17], v[16:17], v[54:55]
	v_pk_mul_f32 v[18:19], v[18:19], v[56:57]
	s_waitcnt vmcnt(3)
	v_pk_mul_f32 v[20:21], v[20:21], v[58:59]
	v_pk_mul_f32 v[22:23], v[22:23], v[60:61]
	s_waitcnt vmcnt(2)
	v_pk_mul_f32 v[24:25], v[24:25], v[62:63]
	v_pk_mul_f32 v[28:29], v[28:29], v[64:65]
	s_waitcnt vmcnt(1)
	v_pk_mul_f32 v[30:31], v[30:31], v[66:67]
	v_pk_mul_f32 v[32:33], v[32:33], v[68:69]
	s_waitcnt vmcnt(0)
	v_pk_mul_f32 v[34:35], v[34:35], v[70:71]
	v_pk_mul_f32 v[36:37], v[36:37], v[72:73]
	s_branch .LBB0_889

.LBB0_897:
	s_andn2_saveexec_b64 s[12:13], s[12:13]
	s_mul_i32 s19, s18, 0xffffffd0
	s_add_i32 s19, s5, s19
	s_lshr_b32 s19, s19, 1
	s_mulk_i32 s19, 0xc0
	v_and_b32_e32 v4, 0x60, v4
	v_add_u32_e32 v5, s19, v4
	s_or_b64 exec, exec, s[12:13]
	v_add_u32_e32 v4, v5, v36
	s_lshl_b32 s12, s18, 5
	v_ashrrev_i32_e32 v5, 31, v4
	v_lshl_add_u64 v[40:41], v[4:5], 2, s[0:1]
	s_or_b32 s13, s12, 1
	v_mad_i64_i32 v[4:5], s[18:19], s12, v250, v[40:41]
	v_mad_i64_i32 v[6:7], s[18:19], s13, v250, v[40:41]
	s_or_b32 s13, s12, 2
	global_load_dword v4, v[4:5], off nt
	s_andn2_b64 vcc, exec, s[10:11]
	global_load_dword v5, v[6:7], off nt
	v_mad_i64_i32 v[6:7], s[18:19], s13, v250, v[40:41]
	s_or_b32 s13, s12, 3
	v_mad_i64_i32 v[8:9], s[18:19], s13, v250, v[40:41]
	s_or_b32 s13, s12, 4
	global_load_dword v6, v[6:7], off nt
	s_nop 0
	global_load_dword v7, v[8:9], off nt
	v_mad_i64_i32 v[8:9], s[18:19], s13, v250, v[40:41]
	s_or_b32 s13, s12, 5
	v_mad_i64_i32 v[10:11], s[18:19], s13, v250, v[40:41]
	s_or_b32 s13, s12, 6
	global_load_dword v8, v[8:9], off nt
	s_nop 0
	global_load_dword v9, v[10:11], off nt
	v_mad_i64_i32 v[10:11], s[18:19], s13, v250, v[40:41]
	s_or_b32 s13, s12, 7
	v_mad_i64_i32 v[12:13], s[18:19], s13, v250, v[40:41]
	s_or_b32 s13, s12, 8
	global_load_dword v10, v[10:11], off nt
	s_nop 0
	global_load_dword v11, v[12:13], off nt
	v_mad_i64_i32 v[12:13], s[18:19], s13, v250, v[40:41]
	s_or_b32 s13, s12, 9
	v_mad_i64_i32 v[14:15], s[18:19], s13, v250, v[40:41]
	s_or_b32 s13, s12, 10
	global_load_dword v12, v[12:13], off nt
	s_nop 0
	global_load_dword v13, v[14:15], off nt
	v_mad_i64_i32 v[14:15], s[18:19], s13, v250, v[40:41]
	s_or_b32 s13, s12, 11
	v_mad_i64_i32 v[16:17], s[18:19], s13, v250, v[40:41]
	s_or_b32 s13, s12, 12
	global_load_dword v14, v[14:15], off nt
	s_nop 0
	global_load_dword v15, v[16:17], off nt
	v_mad_i64_i32 v[16:17], s[18:19], s13, v250, v[40:41]
	s_or_b32 s13, s12, 13
	v_mad_i64_i32 v[18:19], s[18:19], s13, v250, v[40:41]
	s_or_b32 s13, s12, 14
	global_load_dword v16, v[16:17], off nt
	s_nop 0
	global_load_dword v17, v[18:19], off nt
	v_mad_i64_i32 v[18:19], s[18:19], s13, v250, v[40:41]
	s_or_b32 s13, s12, 15
	v_mad_i64_i32 v[20:21], s[18:19], s13, v250, v[40:41]
	s_or_b32 s13, s12, 16
	global_load_dword v18, v[18:19], off nt
	s_nop 0
	global_load_dword v19, v[20:21], off nt
	v_mad_i64_i32 v[20:21], s[18:19], s13, v250, v[40:41]
	s_or_b32 s13, s12, 17
	v_mad_i64_i32 v[22:23], s[18:19], s13, v250, v[40:41]
	s_or_b32 s13, s12, 18
	global_load_dword v20, v[20:21], off nt
	s_nop 0
	global_load_dword v21, v[22:23], off nt
	v_mad_i64_i32 v[22:23], s[18:19], s13, v250, v[40:41]
	s_or_b32 s13, s12, 19
	v_mad_i64_i32 v[24:25], s[18:19], s13, v250, v[40:41]
	s_or_b32 s13, s12, 20
	global_load_dword v22, v[22:23], off nt
	s_nop 0
	global_load_dword v23, v[24:25], off nt
	v_mad_i64_i32 v[24:25], s[18:19], s13, v250, v[40:41]
	s_or_b32 s13, s12, 21
	v_mad_i64_i32 v[26:27], s[18:19], s13, v250, v[40:41]
	s_or_b32 s13, s12, 22
	global_load_dword v24, v[24:25], off nt
	s_nop 0
	global_load_dword v25, v[26:27], off nt
	v_mad_i64_i32 v[26:27], s[18:19], s13, v250, v[40:41]
	s_or_b32 s13, s12, 23
	v_mad_i64_i32 v[28:29], s[18:19], s13, v250, v[40:41]
	s_or_b32 s13, s12, 24
	global_load_dword v26, v[26:27], off nt
	s_nop 0
	global_load_dword v27, v[28:29], off nt
	v_mad_i64_i32 v[28:29], s[18:19], s13, v250, v[40:41]
	s_or_b32 s13, s12, 25
	v_mad_i64_i32 v[30:31], s[18:19], s13, v250, v[40:41]
	s_or_b32 s13, s12, 26
	global_load_dword v28, v[28:29], off nt
	s_nop 0
	global_load_dword v29, v[30:31], off nt
	v_mad_i64_i32 v[30:31], s[18:19], s13, v250, v[40:41]
	s_or_b32 s13, s12, 27
	v_mad_i64_i32 v[32:33], s[18:19], s13, v250, v[40:41]
	s_or_b32 s13, s12, 28
	global_load_dword v30, v[30:31], off nt
	s_nop 0
	global_load_dword v31, v[32:33], off nt
	v_mad_i64_i32 v[32:33], s[18:19], s13, v250, v[40:41]
	s_or_b32 s13, s12, 29
	v_mad_i64_i32 v[34:35], s[18:19], s13, v250, v[40:41]
	s_or_b32 s13, s12, 30
	global_load_dword v32, v[32:33], off nt
	s_nop 0
	global_load_dword v33, v[34:35], off nt
	v_mad_i64_i32 v[34:35], s[18:19], s13, v250, v[40:41]
	s_or_b32 s13, s12, 31
	v_mad_i64_i32 v[40:41], s[18:19], s13, v250, v[40:41]
	global_load_dword v34, v[34:35], off nt
	s_ashr_i32 s13, s12, 31
	global_load_dword v35, v[40:41], off nt
	s_cbranch_vccnz .LBB0_894
	s_lshl_b64 s[18:19], s[12:13], 2
	s_add_u32 s18, s6, s18
	s_addc_u32 s19, s7, s19
	global_load_dwordx4 v[40:43], v0, s[18:19]
	global_load_dwordx4 v[44:47], v0, s[18:19] offset:16
	global_load_dwordx4 v[48:51], v0, s[18:19] offset:32
	global_load_dwordx4 v[52:55], v0, s[18:19] offset:48
	global_load_dwordx4 v[56:59], v0, s[18:19] offset:64
	global_load_dwordx4 v[60:63], v0, s[18:19] offset:80
	global_load_dwordx4 v[64:67], v0, s[18:19] offset:96
	global_load_dwordx4 v[68:71], v0, s[18:19] offset:112
	s_waitcnt vmcnt(7)
	v_pk_mul_f32 v[4:5], v[4:5], v[40:41]
	v_pk_mul_f32 v[6:7], v[6:7], v[42:43]
	s_waitcnt vmcnt(6)
	v_pk_mul_f32 v[8:9], v[8:9], v[44:45]
	v_pk_mul_f32 v[10:11], v[10:11], v[46:47]
	s_waitcnt vmcnt(5)
	v_pk_mul_f32 v[12:13], v[12:13], v[48:49]
	v_pk_mul_f32 v[14:15], v[14:15], v[50:51]
	s_waitcnt vmcnt(4)
	v_pk_mul_f32 v[16:17], v[16:17], v[52:53]
	v_pk_mul_f32 v[18:19], v[18:19], v[54:55]
	s_waitcnt vmcnt(3)
	v_pk_mul_f32 v[20:21], v[20:21], v[56:57]
	v_pk_mul_f32 v[22:23], v[22:23], v[58:59]
	s_waitcnt vmcnt(2)
	v_pk_mul_f32 v[24:25], v[24:25], v[60:61]
	v_pk_mul_f32 v[26:27], v[26:27], v[62:63]
	s_waitcnt vmcnt(1)
	v_pk_mul_f32 v[28:29], v[28:29], v[64:65]
	v_pk_mul_f32 v[30:31], v[30:31], v[66:67]
	s_waitcnt vmcnt(0)
	v_pk_mul_f32 v[32:33], v[32:33], v[68:69]
	v_pk_mul_f32 v[34:35], v[34:35], v[70:71]
	s_branch .LBB0_894

.LBB0_903:
	s_ashr_i32 s8, s5, 31
	s_lshr_b32 s8, s8, 28
	s_add_i32 s8, s5, s8
	s_ashr_i32 s8, s8, 4
	s_lshl_b32 s10, s8, 5
	s_lshl_b32 s8, s8, 10
	s_sub_i32 s8, s6, s8
	v_add_u32_e32 v4, s8, v8
	v_ashrrev_i32_e32 v5, 31, v4
	s_ashr_i32 s11, s10, 31
	v_lshl_add_u64 v[4:5], v[4:5], 2, s[0:1]
	s_lshl_b64 s[12:13], s[10:11], 12
	v_lshl_add_u64 v[10:11], v[4:5], 0, s[12:13]
	s_or_b32 s12, s10, 1
	s_ashr_i32 s13, s12, 31
	s_lshl_b64 s[12:13], s[12:13], 12
	global_load_dword v9, v[10:11], off nt
	v_lshl_add_u64 v[10:11], v[4:5], 0, s[12:13]
	s_or_b32 s12, s10, 2
	s_ashr_i32 s13, s12, 31
	s_lshl_b64 s[12:13], s[12:13], 12
	v_lshl_add_u64 v[12:13], v[4:5], 0, s[12:13]
	s_or_b32 s12, s10, 3
	s_ashr_i32 s13, s12, 31
	s_lshl_b64 s[12:13], s[12:13], 12
	global_load_dword v10, v[10:11], off nt
	s_add_i32 s5, s5, s89
	global_load_dword v11, v[12:13], off nt
	v_lshl_add_u64 v[12:13], v[4:5], 0, s[12:13]
	s_or_b32 s12, s10, 4
	s_ashr_i32 s13, s12, 31
	s_lshl_b64 s[12:13], s[12:13], 12
	v_lshl_add_u64 v[14:15], v[4:5], 0, s[12:13]
	s_or_b32 s12, s10, 5
	s_ashr_i32 s13, s12, 31
	s_lshl_b64 s[12:13], s[12:13], 12
	global_load_dword v12, v[12:13], off nt
	s_add_i32 s6, s6, s7
	global_load_dword v13, v[14:15], off nt
	v_lshl_add_u64 v[14:15], v[4:5], 0, s[12:13]
	s_or_b32 s12, s10, 6
	s_ashr_i32 s13, s12, 31
	s_lshl_b64 s[12:13], s[12:13], 12
	v_lshl_add_u64 v[16:17], v[4:5], 0, s[12:13]
	s_or_b32 s12, s10, 7
	s_ashr_i32 s13, s12, 31
	s_lshl_b64 s[12:13], s[12:13], 12
	global_load_dword v14, v[14:15], off nt
	s_nop 0
	global_load_dword v15, v[16:17], off nt
	v_lshl_add_u64 v[16:17], v[4:5], 0, s[12:13]
	s_or_b32 s12, s10, 8
	s_ashr_i32 s13, s12, 31
	s_lshl_b64 s[12:13], s[12:13], 12
	v_lshl_add_u64 v[18:19], v[4:5], 0, s[12:13]
	s_or_b32 s12, s10, 9
	s_ashr_i32 s13, s12, 31
	s_lshl_b64 s[12:13], s[12:13], 12
	global_load_dword v16, v[16:17], off nt
	s_nop 0
	global_load_dword v17, v[18:19], off nt
	v_lshl_add_u64 v[18:19], v[4:5], 0, s[12:13]
	s_or_b32 s12, s10, 10
	s_ashr_i32 s13, s12, 31
	s_lshl_b64 s[12:13], s[12:13], 12
	v_lshl_add_u64 v[20:21], v[4:5], 0, s[12:13]
	s_or_b32 s12, s10, 11
	s_ashr_i32 s13, s12, 31
	s_lshl_b64 s[12:13], s[12:13], 12
	global_load_dword v18, v[18:19], off nt
	s_nop 0
	global_load_dword v19, v[20:21], off nt
	v_lshl_add_u64 v[20:21], v[4:5], 0, s[12:13]
	s_or_b32 s12, s10, 12
	s_ashr_i32 s13, s12, 31
	s_lshl_b64 s[12:13], s[12:13], 12
	v_lshl_add_u64 v[22:23], v[4:5], 0, s[12:13]
	s_or_b32 s12, s10, 13
	s_ashr_i32 s13, s12, 31
	s_lshl_b64 s[12:13], s[12:13], 12
	global_load_dword v20, v[20:21], off nt
	s_nop 0
	global_load_dword v21, v[22:23], off nt
	v_lshl_add_u64 v[22:23], v[4:5], 0, s[12:13]
	s_or_b32 s12, s10, 14
	s_ashr_i32 s13, s12, 31
	s_lshl_b64 s[12:13], s[12:13], 12
	v_lshl_add_u64 v[24:25], v[4:5], 0, s[12:13]
	s_or_b32 s12, s10, 15
	s_ashr_i32 s13, s12, 31
	s_lshl_b64 s[12:13], s[12:13], 12
	global_load_dword v22, v[22:23], off nt
	s_nop 0
	global_load_dword v23, v[24:25], off nt
	v_lshl_add_u64 v[24:25], v[4:5], 0, s[12:13]
	s_or_b32 s12, s10, 16
	s_ashr_i32 s13, s12, 31
	s_lshl_b64 s[12:13], s[12:13], 12
	v_lshl_add_u64 v[26:27], v[4:5], 0, s[12:13]
	s_or_b32 s12, s10, 17
	s_ashr_i32 s13, s12, 31
	s_lshl_b64 s[12:13], s[12:13], 12
	global_load_dword v24, v[24:25], off nt
	s_nop 0
	global_load_dword v25, v[26:27], off nt
	v_lshl_add_u64 v[26:27], v[4:5], 0, s[12:13]
	s_or_b32 s12, s10, 18
	s_ashr_i32 s13, s12, 31
	s_lshl_b64 s[12:13], s[12:13], 12
	v_lshl_add_u64 v[28:29], v[4:5], 0, s[12:13]
	s_or_b32 s12, s10, 19
	s_ashr_i32 s13, s12, 31
	s_lshl_b64 s[12:13], s[12:13], 12
	global_load_dword v26, v[26:27], off nt
	s_nop 0
	global_load_dword v27, v[28:29], off nt
	v_lshl_add_u64 v[28:29], v[4:5], 0, s[12:13]
	s_or_b32 s12, s10, 20
	s_ashr_i32 s13, s12, 31
	s_lshl_b64 s[12:13], s[12:13], 12
	v_lshl_add_u64 v[30:31], v[4:5], 0, s[12:13]
	s_or_b32 s12, s10, 21
	s_ashr_i32 s13, s12, 31
	s_lshl_b64 s[12:13], s[12:13], 12
	global_load_dword v28, v[28:29], off nt
	s_nop 0
	global_load_dword v29, v[30:31], off nt
	v_lshl_add_u64 v[30:31], v[4:5], 0, s[12:13]
	s_or_b32 s12, s10, 22
	s_ashr_i32 s13, s12, 31
	s_lshl_b64 s[12:13], s[12:13], 12
	v_lshl_add_u64 v[32:33], v[4:5], 0, s[12:13]
	s_or_b32 s12, s10, 23
	s_ashr_i32 s13, s12, 31
	s_lshl_b64 s[12:13], s[12:13], 12
	global_load_dword v30, v[30:31], off nt
	s_nop 0
	global_load_dword v31, v[32:33], off nt
	v_lshl_add_u64 v[32:33], v[4:5], 0, s[12:13]
	s_or_b32 s12, s10, 24
	s_ashr_i32 s13, s12, 31
	s_lshl_b64 s[12:13], s[12:13], 12
	v_lshl_add_u64 v[34:35], v[4:5], 0, s[12:13]
	s_or_b32 s12, s10, 25
	s_ashr_i32 s13, s12, 31
	s_lshl_b64 s[12:13], s[12:13], 12
	global_load_dword v32, v[32:33], off nt
	s_nop 0
	global_load_dword v33, v[34:35], off nt
	v_lshl_add_u64 v[34:35], v[4:5], 0, s[12:13]
	s_or_b32 s12, s10, 26
	s_ashr_i32 s13, s12, 31
	s_lshl_b64 s[12:13], s[12:13], 12
	v_lshl_add_u64 v[36:37], v[4:5], 0, s[12:13]
	s_or_b32 s12, s10, 27
	s_ashr_i32 s13, s12, 31
	s_lshl_b64 s[12:13], s[12:13], 12
	global_load_dword v34, v[34:35], off nt
	s_nop 0
	global_load_dword v35, v[36:37], off nt
	v_lshl_add_u64 v[36:37], v[4:5], 0, s[12:13]
	s_or_b32 s12, s10, 28
	s_ashr_i32 s13, s12, 31
	s_lshl_b64 s[12:13], s[12:13], 12
	v_lshl_add_u64 v[38:39], v[4:5], 0, s[12:13]
	s_or_b32 s12, s10, 29
	s_ashr_i32 s13, s12, 31
	s_lshl_b64 s[12:13], s[12:13], 12
	global_load_dword v36, v[36:37], off nt
	s_nop 0
	global_load_dword v37, v[38:39], off nt
	v_lshl_add_u64 v[38:39], v[4:5], 0, s[12:13]
	s_or_b32 s12, s10, 30
	s_ashr_i32 s13, s12, 31
	s_lshl_b64 s[12:13], s[12:13], 12
	v_lshl_add_u64 v[40:41], v[4:5], 0, s[12:13]
	s_or_b32 s12, s10, 31
	s_ashr_i32 s13, s12, 31
	s_lshl_b64 s[12:13], s[12:13], 12
	global_load_dword v38, v[38:39], off nt
	v_lshl_add_u64 v[4:5], v[4:5], 0, s[12:13]
	global_load_dword v4, v[4:5], off nt
	v_add_u32_e32 v5, 0x400, v1
	global_load_dword v39, v[40:41], off nt
	s_waitcnt vmcnt(30)
	ds_write2_b32 v1, v9, v10 offset1:65
	s_waitcnt vmcnt(28)
	ds_write2_b32 v1, v11, v12 offset0:130 offset1:195
	s_waitcnt vmcnt(26)
	ds_write2_b32 v5, v13, v14 offset0:4 offset1:69
	s_waitcnt vmcnt(24)
	ds_write2_b32 v5, v15, v16 offset0:134 offset1:199
	v_add_u32_e32 v5, 0x800, v1
	s_waitcnt vmcnt(22)
	ds_write2_b32 v5, v17, v18 offset0:8 offset1:73
	s_waitcnt vmcnt(20)
	ds_write2_b32 v5, v19, v20 offset0:138 offset1:203
	v_add_u32_e32 v5, 0xc00, v1
	s_waitcnt vmcnt(18)
	ds_write2_b32 v5, v21, v22 offset0:12 offset1:77
	s_waitcnt vmcnt(16)
	ds_write2_b32 v5, v23, v24 offset0:142 offset1:207
	v_add_u32_e32 v5, 0x1000, v1
	s_waitcnt vmcnt(14)
	ds_write2_b32 v5, v25, v26 offset0:16 offset1:81
	s_waitcnt vmcnt(12)
	ds_write2_b32 v5, v27, v28 offset0:146 offset1:211
	v_add_u32_e32 v5, 0x1400, v1
	s_waitcnt vmcnt(10)
	ds_write2_b32 v5, v29, v30 offset0:20 offset1:85
	s_waitcnt vmcnt(8)
	ds_write2_b32 v5, v31, v32 offset0:150 offset1:215
	v_add_u32_e32 v5, 0x1800, v1
	s_waitcnt vmcnt(6)
	ds_write2_b32 v5, v33, v34 offset0:24 offset1:89
	s_waitcnt vmcnt(4)
	ds_write2_b32 v5, v35, v36 offset0:154 offset1:219
	v_add_u32_e32 v5, 0x1c00, v1
	s_waitcnt vmcnt(2)
	ds_write2_b32 v5, v37, v38 offset0:28 offset1:93
	s_waitcnt vmcnt(0)
	ds_write2_b32 v5, v39, v4 offset0:158 offset1:223
	s_waitcnt lgkmcnt(0)
	v_add_u32_e32 v9, 0x400, v7
	ds_read2_b32 v[14:15], v7 offset1:16
	ds_read2_b32 v[16:17], v7 offset0:65 offset1:81
	ds_read2_b32 v[18:19], v7 offset0:130 offset1:146
	ds_read2_b32 v[20:21], v7 offset0:195 offset1:211
	ds_read2_b32 v[22:23], v9 offset0:4 offset1:20
	ds_read2_b32 v[24:25], v9 offset0:69 offset1:85
	ds_read2_b32 v[26:27], v9 offset0:134 offset1:150
	ds_read2_b32 v[28:29], v9 offset0:199 offset1:215
	v_add_u32_e32 v30, s8, v6
	v_ashrrev_i32_e32 v31, 31, v30
	v_lshl_add_u64 v[4:5], s[10:11], 1, v[2:3]
	v_lshlrev_b64 v[32:33], 12, v[30:31]
	s_waitcnt lgkmcnt(6)
	v_cvt_pk_bf16_f32 v10, v14, v16
	s_waitcnt lgkmcnt(4)
	v_cvt_pk_bf16_f32 v11, v18, v20
	s_waitcnt lgkmcnt(2)
	v_cvt_pk_bf16_f32 v12, v22, v24
	s_waitcnt lgkmcnt(0)
	v_cvt_pk_bf16_f32 v13, v26, v28
	v_lshl_add_u64 v[32:33], v[4:5], 0, v[32:33]
	v_add_u32_e32 v14, 16, v30
	global_store_dwordx4 v[32:33], v[10:13], off
	v_add_u32_e32 v32, 32, v30
	v_ashrrev_i32_e32 v33, 31, v32
	v_cvt_pk_bf16_f32 v10, v15, v17
	v_ashrrev_i32_e32 v15, 31, v14
	v_lshlrev_b64 v[14:15], 12, v[14:15]
	v_cvt_pk_bf16_f32 v11, v19, v21
	v_cvt_pk_bf16_f32 v12, v23, v25
	v_cvt_pk_bf16_f32 v13, v27, v29
	v_lshl_add_u64 v[14:15], v[4:5], 0, v[14:15]
	global_store_dwordx4 v[14:15], v[10:13], off
	ds_read2_b32 v[14:15], v7 offset0:32 offset1:48
	ds_read2_b32 v[16:17], v7 offset0:97 offset1:113
	ds_read2_b32 v[18:19], v7 offset0:162 offset1:178
	ds_read2_b32 v[20:21], v7 offset0:227 offset1:243
	ds_read2_b32 v[22:23], v9 offset0:36 offset1:52
	ds_read2_b32 v[24:25], v9 offset0:101 offset1:117
	ds_read2_b32 v[26:27], v9 offset0:166 offset1:182
	ds_read2_b32 v[28:29], v9 offset0:231 offset1:247
	v_lshlrev_b64 v[32:33], 12, v[32:33]
	s_waitcnt lgkmcnt(6)
	v_cvt_pk_bf16_f32 v10, v14, v16
	s_waitcnt lgkmcnt(4)
	v_cvt_pk_bf16_f32 v11, v18, v20
	s_waitcnt lgkmcnt(2)
	v_cvt_pk_bf16_f32 v12, v22, v24
	s_waitcnt lgkmcnt(0)
	v_cvt_pk_bf16_f32 v13, v26, v28
	v_lshl_add_u64 v[32:33], v[4:5], 0, v[32:33]
	v_add_u32_e32 v14, 48, v30
	global_store_dwordx4 v[32:33], v[10:13], off
	s_cmpk_lt_i32 s5, 0x400
	s_nop 0
	v_cvt_pk_bf16_f32 v10, v15, v17
	v_ashrrev_i32_e32 v15, 31, v14
	v_lshlrev_b64 v[14:15], 12, v[14:15]
	v_cvt_pk_bf16_f32 v11, v19, v21
	v_cvt_pk_bf16_f32 v12, v23, v25
	v_cvt_pk_bf16_f32 v13, v27, v29
	v_lshl_add_u64 v[4:5], v[4:5], 0, v[14:15]
	global_store_dwordx4 v[4:5], v[10:13], off
	s_waitcnt lgkmcnt(0)
	s_cbranch_scc1 .LBB0_903

.LBB0_909:
	s_mul_hi_i32 s12, s9, 0x2aaaaaab
	s_lshr_b32 s13, s12, 31
	s_ashr_i32 s12, s12, 3
	s_add_i32 s13, s12, s13
	s_lshl_b32 s12, s13, 5
	s_mulk_i32 s13, 0xf400
	s_add_i32 s14, s7, s13
	s_and_b32 s13, s14, 0xffffff00
	s_lshr_b32 s15, s14, 2
	v_and_b32_e32 v4, 0xc0, v39
	s_and_b32 s15, s15, 32
	v_or_b32_e32 v5, s13, v1
	v_or3_b32 v4, v5, s15, v4
	v_ashrrev_i32_e32 v5, 31, v4
	v_lshl_add_u64 v[40:41], v[4:5], 2, s[0:1]
	s_or_b32 s13, s12, 1
	v_mad_i64_i32 v[4:5], s[18:19], s12, v250, v[40:41]
	v_mad_i64_i32 v[6:7], s[18:19], s13, v250, v[40:41]
	s_or_b32 s13, s12, 2
	global_load_dword v4, v[4:5], off nt
	s_or_b32 s24, s12, 16
	global_load_dword v5, v[6:7], off nt
	v_mad_i64_i32 v[6:7], s[18:19], s13, v250, v[40:41]
	s_or_b32 s13, s12, 3
	v_mad_i64_i32 v[8:9], s[18:19], s13, v250, v[40:41]
	s_or_b32 s13, s12, 4
	global_load_dword v6, v[6:7], off nt
	s_andn2_b64 vcc, exec, s[10:11]
	global_load_dword v7, v[8:9], off nt
	v_mad_i64_i32 v[8:9], s[18:19], s13, v250, v[40:41]
	s_or_b32 s13, s12, 5
	v_mad_i64_i32 v[10:11], s[18:19], s13, v250, v[40:41]
	s_or_b32 s13, s12, 6
	global_load_dword v8, v[8:9], off nt
	s_nop 0
	global_load_dword v9, v[10:11], off nt
	v_mad_i64_i32 v[10:11], s[18:19], s13, v250, v[40:41]
	s_or_b32 s13, s12, 7
	v_mad_i64_i32 v[12:13], s[18:19], s13, v250, v[40:41]
	s_or_b32 s13, s12, 8
	global_load_dword v10, v[10:11], off nt
	s_nop 0
	global_load_dword v11, v[12:13], off nt
	v_mad_i64_i32 v[12:13], s[18:19], s13, v250, v[40:41]
	s_or_b32 s13, s12, 9
	v_mad_i64_i32 v[14:15], s[18:19], s13, v250, v[40:41]
	s_or_b32 s13, s12, 10
	global_load_dword v12, v[12:13], off nt
	s_nop 0
	global_load_dword v13, v[14:15], off nt
	v_mad_i64_i32 v[14:15], s[18:19], s13, v250, v[40:41]
	s_or_b32 s13, s12, 11
	v_mad_i64_i32 v[16:17], s[18:19], s13, v250, v[40:41]
	s_or_b32 s13, s12, 12
	global_load_dword v14, v[14:15], off nt
	s_nop 0
	global_load_dword v15, v[16:17], off nt
	v_mad_i64_i32 v[16:17], s[18:19], s13, v250, v[40:41]
	s_or_b32 s13, s12, 13
	v_mad_i64_i32 v[18:19], s[18:19], s13, v250, v[40:41]
	s_or_b32 s13, s12, 14
	global_load_dword v16, v[16:17], off nt
	s_nop 0
	global_load_dword v17, v[18:19], off nt
	v_mad_i64_i32 v[18:19], s[18:19], s13, v250, v[40:41]
	s_or_b32 s13, s12, 15
	v_mad_i64_i32 v[20:21], s[18:19], s13, v250, v[40:41]
	s_or_b32 s13, s12, 17
	global_load_dword v18, v[18:19], off nt
	v_mad_i64_i32 v[22:23], s[18:19], s13, v250, v[40:41]
	global_load_dword v19, v[20:21], off nt
	v_mad_i64_i32 v[20:21], s[18:19], s24, v250, v[40:41]
	s_or_b32 s13, s12, 18
	global_load_dword v20, v[20:21], off nt
	s_nop 0
	global_load_dword v21, v[22:23], off nt
	v_mad_i64_i32 v[22:23], s[18:19], s13, v250, v[40:41]
	s_or_b32 s13, s12, 19
	v_mad_i64_i32 v[24:25], s[18:19], s13, v250, v[40:41]
	s_or_b32 s13, s12, 20
	global_load_dword v22, v[22:23], off nt
	s_nop 0
	global_load_dword v23, v[24:25], off nt
	v_mad_i64_i32 v[24:25], s[18:19], s13, v250, v[40:41]
	s_or_b32 s13, s12, 21
	v_mad_i64_i32 v[26:27], s[18:19], s13, v250, v[40:41]
	s_or_b32 s13, s12, 22
	global_load_dword v24, v[24:25], off nt
	s_nop 0
	global_load_dword v25, v[26:27], off nt
	v_mad_i64_i32 v[26:27], s[18:19], s13, v250, v[40:41]
	s_or_b32 s13, s12, 23
	v_mad_i64_i32 v[28:29], s[18:19], s13, v250, v[40:41]
	s_or_b32 s13, s12, 24
	global_load_dword v26, v[26:27], off nt
	s_nop 0
	global_load_dword v27, v[28:29], off nt
	v_mad_i64_i32 v[28:29], s[18:19], s13, v250, v[40:41]
	s_or_b32 s13, s12, 25
	v_mad_i64_i32 v[30:31], s[18:19], s13, v250, v[40:41]
	s_or_b32 s13, s12, 26
	global_load_dword v28, v[28:29], off nt
	s_nop 0
	global_load_dword v29, v[30:31], off nt
	v_mad_i64_i32 v[30:31], s[18:19], s13, v250, v[40:41]
	s_or_b32 s13, s12, 27
	v_mad_i64_i32 v[32:33], s[18:19], s13, v250, v[40:41]
	s_or_b32 s13, s12, 28
	global_load_dword v30, v[30:31], off nt
	s_nop 0
	global_load_dword v31, v[32:33], off nt
	v_mad_i64_i32 v[32:33], s[18:19], s13, v250, v[40:41]
	s_or_b32 s13, s12, 29
	v_mad_i64_i32 v[34:35], s[18:19], s13, v250, v[40:41]
	s_or_b32 s13, s12, 30
	global_load_dword v32, v[32:33], off nt
	s_nop 0
	global_load_dword v33, v[34:35], off nt
	v_mad_i64_i32 v[34:35], s[18:19], s13, v250, v[40:41]
	s_or_b32 s13, s12, 31
	v_mad_i64_i32 v[40:41], s[18:19], s13, v250, v[40:41]
	global_load_dword v34, v[34:35], off nt
	s_ashr_i32 s13, s12, 31
	global_load_dword v35, v[40:41], off nt
	s_cbranch_vccnz .LBB0_908
	s_ashr_i32 s25, s24, 31
	s_lshl_b64 s[18:19], s[12:13], 2
	s_add_u32 s18, s4, s18
	s_addc_u32 s19, s5, s19
	global_load_dwordx4 v[40:43], v0, s[18:19]
	global_load_dwordx4 v[44:47], v0, s[18:19] offset:16
	global_load_dwordx4 v[48:51], v0, s[18:19] offset:48
	global_load_dwordx4 v[52:55], v0, s[18:19] offset:32
	s_lshl_b64 s[18:19], s[24:25], 2
	s_add_u32 s18, s4, s18
	s_addc_u32 s19, s5, s19
	global_load_dwordx4 v[56:59], v0, s[18:19]
	global_load_dwordx4 v[60:63], v0, s[18:19] offset:16
	global_load_dwordx4 v[64:67], v0, s[18:19] offset:32
	global_load_dwordx4 v[68:71], v0, s[18:19] offset:48
	s_waitcnt vmcnt(7)
	v_pk_mul_f32 v[4:5], v[4:5], v[40:41]
	v_pk_mul_f32 v[6:7], v[6:7], v[42:43]
	s_waitcnt vmcnt(6)
	v_pk_mul_f32 v[8:9], v[8:9], v[44:45]
	v_pk_mul_f32 v[10:11], v[10:11], v[46:47]
	s_waitcnt vmcnt(4)
	v_pk_mul_f32 v[12:13], v[12:13], v[52:53]
	v_pk_mul_f32 v[14:15], v[14:15], v[54:55]
	v_pk_mul_f32 v[16:17], v[16:17], v[48:49]
	v_pk_mul_f32 v[18:19], v[18:19], v[50:51]
	s_waitcnt vmcnt(3)
	v_pk_mul_f32 v[20:21], v[20:21], v[56:57]
	v_pk_mul_f32 v[22:23], v[22:23], v[58:59]
	s_waitcnt vmcnt(2)
	v_pk_mul_f32 v[24:25], v[24:25], v[60:61]
	v_pk_mul_f32 v[26:27], v[26:27], v[62:63]
	s_waitcnt vmcnt(1)
	v_pk_mul_f32 v[28:29], v[28:29], v[64:65]
	v_pk_mul_f32 v[30:31], v[30:31], v[66:67]
	s_waitcnt vmcnt(0)
	v_pk_mul_f32 v[32:33], v[32:33], v[68:69]
	v_pk_mul_f32 v[34:35], v[34:35], v[70:71]
	s_branch .LBB0_908

.LBB0_913:
	s_ashr_i32 s7, s6, 31
	s_lshr_b32 s7, s7, 28
	s_add_i32 s7, s6, s7
	s_ashr_i32 s7, s7, 4
	s_lshl_b32 s10, s7, 5
	s_lshl_b32 s7, s7, 10
	s_sub_i32 s7, s4, s7
	v_add_u32_e32 v4, s7, v8
	v_ashrrev_i32_e32 v5, 31, v4
	s_ashr_i32 s11, s10, 31
	v_lshl_add_u64 v[4:5], v[4:5], 2, s[0:1]
	s_lshl_b64 s[8:9], s[10:11], 12
	v_lshl_add_u64 v[10:11], v[4:5], 0, s[8:9]
	s_or_b32 s8, s10, 1
	s_ashr_i32 s9, s8, 31
	s_lshl_b64 s[8:9], s[8:9], 12
	global_load_dword v9, v[10:11], off nt
	v_lshl_add_u64 v[10:11], v[4:5], 0, s[8:9]
	s_or_b32 s8, s10, 2
	s_ashr_i32 s9, s8, 31
	s_lshl_b64 s[8:9], s[8:9], 12
	v_lshl_add_u64 v[12:13], v[4:5], 0, s[8:9]
	s_or_b32 s8, s10, 3
	s_ashr_i32 s9, s8, 31
	s_lshl_b64 s[8:9], s[8:9], 12
	global_load_dword v10, v[10:11], off nt
	s_or_b32 s12, s10, 31
	global_load_dword v11, v[12:13], off nt
	v_lshl_add_u64 v[12:13], v[4:5], 0, s[8:9]
	s_or_b32 s8, s10, 4
	s_ashr_i32 s9, s8, 31
	s_lshl_b64 s[8:9], s[8:9], 12
	v_lshl_add_u64 v[14:15], v[4:5], 0, s[8:9]
	s_or_b32 s8, s10, 5
	s_ashr_i32 s9, s8, 31
	s_lshl_b64 s[8:9], s[8:9], 12
	global_load_dword v12, v[12:13], off nt
	s_ashr_i32 s13, s12, 31
	global_load_dword v13, v[14:15], off nt
	v_lshl_add_u64 v[14:15], v[4:5], 0, s[8:9]
	s_or_b32 s8, s10, 6
	s_ashr_i32 s9, s8, 31
	s_lshl_b64 s[8:9], s[8:9], 12
	v_lshl_add_u64 v[16:17], v[4:5], 0, s[8:9]
	s_or_b32 s8, s10, 7
	s_ashr_i32 s9, s8, 31
	s_lshl_b64 s[8:9], s[8:9], 12
	global_load_dword v14, v[14:15], off nt
	s_lshl_b64 s[12:13], s[12:13], 12
	global_load_dword v15, v[16:17], off nt
	v_lshl_add_u64 v[16:17], v[4:5], 0, s[8:9]
	s_or_b32 s8, s10, 8
	s_ashr_i32 s9, s8, 31
	s_lshl_b64 s[8:9], s[8:9], 12
	v_lshl_add_u64 v[18:19], v[4:5], 0, s[8:9]
	s_or_b32 s8, s10, 9
	s_ashr_i32 s9, s8, 31
	s_lshl_b64 s[8:9], s[8:9], 12
	global_load_dword v16, v[16:17], off nt
	s_add_i32 s6, s6, s89
	global_load_dword v17, v[18:19], off nt
	v_lshl_add_u64 v[18:19], v[4:5], 0, s[8:9]
	s_or_b32 s8, s10, 10
	s_ashr_i32 s9, s8, 31
	s_lshl_b64 s[8:9], s[8:9], 12
	v_lshl_add_u64 v[20:21], v[4:5], 0, s[8:9]
	s_or_b32 s8, s10, 11
	s_ashr_i32 s9, s8, 31
	s_lshl_b64 s[8:9], s[8:9], 12
	global_load_dword v18, v[18:19], off nt
	s_add_i32 s4, s4, s5
	global_load_dword v19, v[20:21], off nt
	v_lshl_add_u64 v[20:21], v[4:5], 0, s[8:9]
	s_or_b32 s8, s10, 12
	s_ashr_i32 s9, s8, 31
	s_lshl_b64 s[8:9], s[8:9], 12
	v_lshl_add_u64 v[22:23], v[4:5], 0, s[8:9]
	s_or_b32 s8, s10, 13
	s_ashr_i32 s9, s8, 31
	s_lshl_b64 s[8:9], s[8:9], 12
	global_load_dword v20, v[20:21], off nt
	s_nop 0
	global_load_dword v21, v[22:23], off nt
	v_lshl_add_u64 v[22:23], v[4:5], 0, s[8:9]
	s_or_b32 s8, s10, 14
	s_ashr_i32 s9, s8, 31
	s_lshl_b64 s[8:9], s[8:9], 12
	v_lshl_add_u64 v[24:25], v[4:5], 0, s[8:9]
	s_or_b32 s8, s10, 15
	s_ashr_i32 s9, s8, 31
	s_lshl_b64 s[8:9], s[8:9], 12
	global_load_dword v22, v[22:23], off nt
	s_nop 0
	global_load_dword v23, v[24:25], off nt
	v_lshl_add_u64 v[24:25], v[4:5], 0, s[8:9]
	s_or_b32 s8, s10, 16
	s_ashr_i32 s9, s8, 31
	s_lshl_b64 s[8:9], s[8:9], 12
	v_lshl_add_u64 v[26:27], v[4:5], 0, s[8:9]
	s_or_b32 s8, s10, 17
	s_ashr_i32 s9, s8, 31
	s_lshl_b64 s[8:9], s[8:9], 12
	global_load_dword v24, v[24:25], off nt
	s_nop 0
	global_load_dword v25, v[26:27], off nt
	v_lshl_add_u64 v[26:27], v[4:5], 0, s[8:9]
	s_or_b32 s8, s10, 18
	s_ashr_i32 s9, s8, 31
	s_lshl_b64 s[8:9], s[8:9], 12
	v_lshl_add_u64 v[28:29], v[4:5], 0, s[8:9]
	s_or_b32 s8, s10, 19
	s_ashr_i32 s9, s8, 31
	s_lshl_b64 s[8:9], s[8:9], 12
	global_load_dword v26, v[26:27], off nt
	s_nop 0
	global_load_dword v27, v[28:29], off nt
	v_lshl_add_u64 v[28:29], v[4:5], 0, s[8:9]
	s_or_b32 s8, s10, 20
	s_ashr_i32 s9, s8, 31
	s_lshl_b64 s[8:9], s[8:9], 12
	v_lshl_add_u64 v[30:31], v[4:5], 0, s[8:9]
	s_or_b32 s8, s10, 21
	s_ashr_i32 s9, s8, 31
	s_lshl_b64 s[8:9], s[8:9], 12
	global_load_dword v28, v[28:29], off nt
	s_nop 0
	global_load_dword v29, v[30:31], off nt
	v_lshl_add_u64 v[30:31], v[4:5], 0, s[8:9]
	s_or_b32 s8, s10, 22
	s_ashr_i32 s9, s8, 31
	s_lshl_b64 s[8:9], s[8:9], 12
	v_lshl_add_u64 v[32:33], v[4:5], 0, s[8:9]
	s_or_b32 s8, s10, 23
	s_ashr_i32 s9, s8, 31
	s_lshl_b64 s[8:9], s[8:9], 12
	global_load_dword v30, v[30:31], off nt
	s_nop 0
	global_load_dword v31, v[32:33], off nt
	v_lshl_add_u64 v[32:33], v[4:5], 0, s[8:9]
	s_or_b32 s8, s10, 24
	s_ashr_i32 s9, s8, 31
	s_lshl_b64 s[8:9], s[8:9], 12
	v_lshl_add_u64 v[34:35], v[4:5], 0, s[8:9]
	s_or_b32 s8, s10, 25
	s_ashr_i32 s9, s8, 31
	s_lshl_b64 s[8:9], s[8:9], 12
	global_load_dword v32, v[32:33], off nt
	s_nop 0
	global_load_dword v33, v[34:35], off nt
	v_lshl_add_u64 v[34:35], v[4:5], 0, s[8:9]
	s_or_b32 s8, s10, 26
	s_ashr_i32 s9, s8, 31
	s_lshl_b64 s[8:9], s[8:9], 12
	v_lshl_add_u64 v[36:37], v[4:5], 0, s[8:9]
	s_or_b32 s8, s10, 27
	s_ashr_i32 s9, s8, 31
	s_lshl_b64 s[8:9], s[8:9], 12
	global_load_dword v34, v[34:35], off nt
	s_nop 0
	global_load_dword v35, v[36:37], off nt
	v_lshl_add_u64 v[36:37], v[4:5], 0, s[8:9]
	s_or_b32 s8, s10, 28
	s_ashr_i32 s9, s8, 31
	s_lshl_b64 s[8:9], s[8:9], 12
	v_lshl_add_u64 v[38:39], v[4:5], 0, s[8:9]
	s_or_b32 s8, s10, 29
	s_ashr_i32 s9, s8, 31
	s_lshl_b64 s[8:9], s[8:9], 12
	global_load_dword v36, v[36:37], off nt
	s_nop 0
	global_load_dword v37, v[38:39], off nt
	v_lshl_add_u64 v[38:39], v[4:5], 0, s[8:9]
	s_or_b32 s8, s10, 30
	s_ashr_i32 s9, s8, 31
	s_lshl_b64 s[8:9], s[8:9], 12
	global_load_dword v38, v[38:39], off nt
	v_lshl_add_u64 v[40:41], v[4:5], 0, s[8:9]
	v_lshl_add_u64 v[4:5], v[4:5], 0, s[12:13]
	global_load_dword v4, v[4:5], off nt
	v_add_u32_e32 v5, 0x400, v1
	global_load_dword v39, v[40:41], off nt
	s_waitcnt vmcnt(30)
	ds_write2_b32 v1, v9, v10 offset1:65
	s_waitcnt vmcnt(28)
	ds_write2_b32 v1, v11, v12 offset0:130 offset1:195
	s_waitcnt vmcnt(26)
	ds_write2_b32 v5, v13, v14 offset0:4 offset1:69
	s_waitcnt vmcnt(24)
	ds_write2_b32 v5, v15, v16 offset0:134 offset1:199
	v_add_u32_e32 v5, 0x800, v1
	s_waitcnt vmcnt(22)
	ds_write2_b32 v5, v17, v18 offset0:8 offset1:73
	s_waitcnt vmcnt(20)
	ds_write2_b32 v5, v19, v20 offset0:138 offset1:203
	v_add_u32_e32 v5, 0xc00, v1
	s_waitcnt vmcnt(18)
	ds_write2_b32 v5, v21, v22 offset0:12 offset1:77
	s_waitcnt vmcnt(16)
	ds_write2_b32 v5, v23, v24 offset0:142 offset1:207
	v_add_u32_e32 v5, 0x1000, v1
	s_waitcnt vmcnt(14)
	ds_write2_b32 v5, v25, v26 offset0:16 offset1:81
	s_waitcnt vmcnt(12)
	ds_write2_b32 v5, v27, v28 offset0:146 offset1:211
	v_add_u32_e32 v5, 0x1400, v1
	s_waitcnt vmcnt(10)
	ds_write2_b32 v5, v29, v30 offset0:20 offset1:85
	s_waitcnt vmcnt(8)
	ds_write2_b32 v5, v31, v32 offset0:150 offset1:215
	v_add_u32_e32 v5, 0x1800, v1
	s_waitcnt vmcnt(6)
	ds_write2_b32 v5, v33, v34 offset0:24 offset1:89
	s_waitcnt vmcnt(4)
	ds_write2_b32 v5, v35, v36 offset0:154 offset1:219
	v_add_u32_e32 v5, 0x1c00, v1
	s_waitcnt vmcnt(2)
	ds_write2_b32 v5, v37, v38 offset0:28 offset1:93
	s_waitcnt vmcnt(0)
	ds_write2_b32 v5, v39, v4 offset0:158 offset1:223
	s_waitcnt lgkmcnt(0)
	v_add_u32_e32 v9, 0x400, v7
	ds_read2_b32 v[14:15], v7 offset1:16
	ds_read2_b32 v[16:17], v7 offset0:65 offset1:81
	ds_read2_b32 v[18:19], v7 offset0:130 offset1:146
	ds_read2_b32 v[20:21], v7 offset0:195 offset1:211
	ds_read2_b32 v[22:23], v9 offset0:4 offset1:20
	ds_read2_b32 v[24:25], v9 offset0:69 offset1:85
	ds_read2_b32 v[26:27], v9 offset0:134 offset1:150
	ds_read2_b32 v[28:29], v9 offset0:199 offset1:215
	v_add_u32_e32 v30, s7, v6
	v_ashrrev_i32_e32 v31, 31, v30
	v_lshl_add_u64 v[4:5], s[10:11], 1, v[2:3]
	v_lshlrev_b64 v[32:33], 11, v[30:31]
	s_waitcnt lgkmcnt(6)
	v_cvt_pk_bf16_f32 v10, v14, v16
	s_waitcnt lgkmcnt(4)
	v_cvt_pk_bf16_f32 v11, v18, v20
	s_waitcnt lgkmcnt(2)
	v_cvt_pk_bf16_f32 v12, v22, v24
	s_waitcnt lgkmcnt(0)
	v_cvt_pk_bf16_f32 v13, v26, v28
	v_lshl_add_u64 v[32:33], v[4:5], 0, v[32:33]
	v_add_u32_e32 v14, 16, v30
	global_store_dwordx4 v[32:33], v[10:13], off
	v_add_u32_e32 v32, 32, v30
	v_ashrrev_i32_e32 v33, 31, v32
	v_cvt_pk_bf16_f32 v10, v15, v17
	v_ashrrev_i32_e32 v15, 31, v14
	v_lshlrev_b64 v[14:15], 11, v[14:15]
	v_cvt_pk_bf16_f32 v11, v19, v21
	v_cvt_pk_bf16_f32 v12, v23, v25
	v_cvt_pk_bf16_f32 v13, v27, v29
	v_lshl_add_u64 v[14:15], v[4:5], 0, v[14:15]
	global_store_dwordx4 v[14:15], v[10:13], off
	ds_read2_b32 v[14:15], v7 offset0:32 offset1:48
	ds_read2_b32 v[16:17], v7 offset0:97 offset1:113
	ds_read2_b32 v[18:19], v7 offset0:162 offset1:178
	ds_read2_b32 v[20:21], v7 offset0:227 offset1:243
	ds_read2_b32 v[22:23], v9 offset0:36 offset1:52
	ds_read2_b32 v[24:25], v9 offset0:101 offset1:117
	ds_read2_b32 v[26:27], v9 offset0:166 offset1:182
	ds_read2_b32 v[28:29], v9 offset0:231 offset1:247
	v_lshlrev_b64 v[32:33], 11, v[32:33]
	s_waitcnt lgkmcnt(6)
	v_cvt_pk_bf16_f32 v10, v14, v16
	s_waitcnt lgkmcnt(4)
	v_cvt_pk_bf16_f32 v11, v18, v20
	s_waitcnt lgkmcnt(2)
	v_cvt_pk_bf16_f32 v12, v22, v24
	s_waitcnt lgkmcnt(0)
	v_cvt_pk_bf16_f32 v13, v26, v28
	v_lshl_add_u64 v[32:33], v[4:5], 0, v[32:33]
	v_add_u32_e32 v14, 48, v30
	global_store_dwordx4 v[32:33], v[10:13], off
	s_cmpk_gt_i32 s6, 0x1ff
	s_nop 0
	v_cvt_pk_bf16_f32 v10, v15, v17
	v_ashrrev_i32_e32 v15, 31, v14
	v_lshlrev_b64 v[14:15], 11, v[14:15]
	v_cvt_pk_bf16_f32 v11, v19, v21
	v_cvt_pk_bf16_f32 v12, v23, v25
	v_cvt_pk_bf16_f32 v13, v27, v29
	v_lshl_add_u64 v[4:5], v[4:5], 0, v[14:15]
	global_store_dwordx4 v[4:5], v[10:13], off
	s_waitcnt lgkmcnt(0)
	s_cbranch_scc0 .LBB0_913
